# P0 adaLN: SiLU staging loop unrolled with 18 loads in flight; GEMV rewritten straight-line with weight-row loads 48 deep ahead of the FMAs (was vmcnt(0) after every 8 loads)
# speedup vs baseline: 1.0128x; 1.0011x over previous
; #define LAS __attribute__((address_space(3)))
; DI void phase_prologue(const Params& p, LAS unsigned char* lds, int tid, int lane, int wave) {
;     ...
;     for (int item = blockIdx.x; item < 192; item += gridDim.x) {
;         const int l = item / 96, cgp = item - l * 96;
;         LAS float* sl = (LAS float*)lds; LAS float* part = sl + 9 * 1024;
;         for (int i = tid; i < 9 * 1024; i += 512) { const int r = i >> 10, k = i & 1023; const float cv = r < 8 ? p.in[1][r * 1024 + k] : p.in[3][k]; sl[i] = cv / (1.f + __expf(-cv)); }
.LBB0_15:
	global_load_dword v13, v[2:3], off
	v_lshl_add_u64 v[2:3], v[2:3], 0, s[10:11]
	global_load_dword v14, v[2:3], off
	v_lshl_add_u64 v[2:3], v[2:3], 0, s[10:11]
	global_load_dword v15, v[2:3], off
	v_lshl_add_u64 v[2:3], v[2:3], 0, s[10:11]
	global_load_dword v16, v[2:3], off
	v_lshl_add_u64 v[2:3], v[2:3], 0, s[10:11]
	global_load_dword v17, v[2:3], off
	v_lshl_add_u64 v[2:3], v[2:3], 0, s[10:11]
	global_load_dword v18, v[2:3], off
	v_lshl_add_u64 v[2:3], v[2:3], 0, s[10:11]
	global_load_dword v19, v[2:3], off
	v_lshl_add_u64 v[2:3], v[2:3], 0, s[10:11]
	global_load_dword v20, v[2:3], off
	v_lshl_add_u64 v[2:3], v[2:3], 0, s[10:11]
	global_load_dword v21, v[2:3], off
	v_lshl_add_u64 v[2:3], v[2:3], 0, s[10:11]
	global_load_dword v22, v[2:3], off
	v_lshl_add_u64 v[2:3], v[2:3], 0, s[10:11]
	global_load_dword v23, v[2:3], off
	v_lshl_add_u64 v[2:3], v[2:3], 0, s[10:11]
	global_load_dword v24, v[2:3], off
	v_lshl_add_u64 v[2:3], v[2:3], 0, s[10:11]
	global_load_dword v25, v[2:3], off
	v_lshl_add_u64 v[2:3], v[2:3], 0, s[10:11]
	global_load_dword v26, v[2:3], off
	v_lshl_add_u64 v[2:3], v[2:3], 0, s[10:11]
	global_load_dword v27, v[2:3], off
	v_lshl_add_u64 v[2:3], v[2:3], 0, s[10:11]
	global_load_dword v28, v[2:3], off
	v_lshl_add_u64 v[2:3], v[2:3], 0, s[10:11]
	v_lshlrev_b32_e32 v54, 2, v5
	s_waitcnt lgkmcnt(0)
	v_lshl_add_u64 v[6:7], s[70:71], 0, v[54:55]
	global_load_dword v29, v[6:7], off
	global_load_dword v30, v[6:7], off offset:2048
	s_waitcnt vmcnt(17)
	v_mul_f32_e32 v7, 0xbfb8aa3b, v13
	v_exp_f32_e32 v7, v7
	s_nop 0
	v_add_f32_e32 v7, 1.0, v7
	v_div_scale_f32 v8, s[60:61], v7, v7, v13
	v_rcp_f32_e32 v9, v8
	v_div_scale_f32 v10, vcc, v13, v7, v13
	v_fma_f32 v11, -v8, v9, 1.0
	v_fmac_f32_e32 v9, v11, v9
	v_mul_f32_e32 v11, v10, v9
	v_fma_f32 v12, -v8, v11, v10
	v_fmac_f32_e32 v11, v12, v9
	v_fma_f32 v8, -v8, v11, v10
	v_div_fmas_f32 v8, v8, v9, v11
	v_div_fixup_f32 v6, v8, v7, v13
	ds_write_b32 v4, v6
	s_waitcnt vmcnt(16)
	v_mul_f32_e32 v7, 0xbfb8aa3b, v14
	v_exp_f32_e32 v7, v7
	s_nop 0
	v_add_f32_e32 v7, 1.0, v7
	v_div_scale_f32 v8, s[60:61], v7, v7, v14
	v_rcp_f32_e32 v9, v8
	v_div_scale_f32 v10, vcc, v14, v7, v14
	v_fma_f32 v11, -v8, v9, 1.0
	v_fmac_f32_e32 v9, v11, v9
	v_mul_f32_e32 v11, v10, v9
	v_fma_f32 v12, -v8, v11, v10
	v_fmac_f32_e32 v11, v12, v9
	v_fma_f32 v8, -v8, v11, v10
	v_div_fmas_f32 v8, v8, v9, v11
	v_div_fixup_f32 v6, v8, v7, v14
	ds_write_b32 v4, v6 offset:2048
	s_waitcnt vmcnt(15)
	v_mul_f32_e32 v7, 0xbfb8aa3b, v15
	v_exp_f32_e32 v7, v7
	s_nop 0
	v_add_f32_e32 v7, 1.0, v7
	v_div_scale_f32 v8, s[60:61], v7, v7, v15
	v_rcp_f32_e32 v9, v8
	v_div_scale_f32 v10, vcc, v15, v7, v15
	v_fma_f32 v11, -v8, v9, 1.0
	v_fmac_f32_e32 v9, v11, v9
	v_mul_f32_e32 v11, v10, v9
	v_fma_f32 v12, -v8, v11, v10
	v_fmac_f32_e32 v11, v12, v9
	v_fma_f32 v8, -v8, v11, v10
	v_div_fmas_f32 v8, v8, v9, v11
	v_div_fixup_f32 v6, v8, v7, v15
	ds_write_b32 v4, v6 offset:4096
	s_waitcnt vmcnt(14)
	v_mul_f32_e32 v7, 0xbfb8aa3b, v16
	v_exp_f32_e32 v7, v7
	s_nop 0
	v_add_f32_e32 v7, 1.0, v7
	v_div_scale_f32 v8, s[60:61], v7, v7, v16
	v_rcp_f32_e32 v9, v8
	v_div_scale_f32 v10, vcc, v16, v7, v16
	v_fma_f32 v11, -v8, v9, 1.0
	v_fmac_f32_e32 v9, v11, v9
	v_mul_f32_e32 v11, v10, v9
	v_fma_f32 v12, -v8, v11, v10
	v_fmac_f32_e32 v11, v12, v9
	v_fma_f32 v8, -v8, v11, v10
	v_div_fmas_f32 v8, v8, v9, v11
	v_div_fixup_f32 v6, v8, v7, v16
	ds_write_b32 v4, v6 offset:6144
	s_waitcnt vmcnt(13)
	v_mul_f32_e32 v7, 0xbfb8aa3b, v17
	v_exp_f32_e32 v7, v7
	s_nop 0
	v_add_f32_e32 v7, 1.0, v7
	v_div_scale_f32 v8, s[60:61], v7, v7, v17
	v_rcp_f32_e32 v9, v8
	v_div_scale_f32 v10, vcc, v17, v7, v17
	v_fma_f32 v11, -v8, v9, 1.0
	v_fmac_f32_e32 v9, v11, v9
	v_mul_f32_e32 v11, v10, v9
	v_fma_f32 v12, -v8, v11, v10
	v_fmac_f32_e32 v11, v12, v9
	v_fma_f32 v8, -v8, v11, v10
	v_div_fmas_f32 v8, v8, v9, v11
	v_div_fixup_f32 v6, v8, v7, v17
	ds_write_b32 v4, v6 offset:8192
	s_waitcnt vmcnt(12)
	v_mul_f32_e32 v7, 0xbfb8aa3b, v18
	v_exp_f32_e32 v7, v7
	s_nop 0
	v_add_f32_e32 v7, 1.0, v7
	v_div_scale_f32 v8, s[60:61], v7, v7, v18
	v_rcp_f32_e32 v9, v8
	v_div_scale_f32 v10, vcc, v18, v7, v18
	v_fma_f32 v11, -v8, v9, 1.0
	v_fmac_f32_e32 v9, v11, v9
	v_mul_f32_e32 v11, v10, v9
	v_fma_f32 v12, -v8, v11, v10
	v_fmac_f32_e32 v11, v12, v9
	v_fma_f32 v8, -v8, v11, v10
	v_div_fmas_f32 v8, v8, v9, v11
	v_div_fixup_f32 v6, v8, v7, v18
	ds_write_b32 v4, v6 offset:10240
	s_waitcnt vmcnt(11)
	v_mul_f32_e32 v7, 0xbfb8aa3b, v19
	v_exp_f32_e32 v7, v7
	s_nop 0
	v_add_f32_e32 v7, 1.0, v7
	v_div_scale_f32 v8, s[60:61], v7, v7, v19
	v_rcp_f32_e32 v9, v8
	v_div_scale_f32 v10, vcc, v19, v7, v19
	v_fma_f32 v11, -v8, v9, 1.0
	v_fmac_f32_e32 v9, v11, v9
	v_mul_f32_e32 v11, v10, v9
	v_fma_f32 v12, -v8, v11, v10
	v_fmac_f32_e32 v11, v12, v9
	v_fma_f32 v8, -v8, v11, v10
	v_div_fmas_f32 v8, v8, v9, v11
	v_div_fixup_f32 v6, v8, v7, v19
	ds_write_b32 v4, v6 offset:12288
	s_waitcnt vmcnt(10)
	v_mul_f32_e32 v7, 0xbfb8aa3b, v20
	v_exp_f32_e32 v7, v7
	s_nop 0
	v_add_f32_e32 v7, 1.0, v7
	v_div_scale_f32 v8, s[60:61], v7, v7, v20
	v_rcp_f32_e32 v9, v8
	v_div_scale_f32 v10, vcc, v20, v7, v20
	v_fma_f32 v11, -v8, v9, 1.0
	v_fmac_f32_e32 v9, v11, v9
	v_mul_f32_e32 v11, v10, v9
	v_fma_f32 v12, -v8, v11, v10
	v_fmac_f32_e32 v11, v12, v9
	v_fma_f32 v8, -v8, v11, v10
	v_div_fmas_f32 v8, v8, v9, v11
	v_div_fixup_f32 v6, v8, v7, v20
	ds_write_b32 v4, v6 offset:14336
	s_waitcnt vmcnt(9)
; DI void phase_prologue(const Params& p, LAS unsigned char* lds, int tid, int lane, int wave) {
;     ...
;         for (int i = tid; i < 9 * 1024; i += 512) { const int r = i >> 10, k = i & 1023; const float cv = r < 8 ? p.in[1][r * 1024 + k] : p.in[3][k]; sl[i] = cv / (1.f + __expf(-cv)); }
	v_mul_f32_e32 v7, 0xbfb8aa3b, v21
	v_exp_f32_e32 v7, v7
	s_nop 0
	v_add_f32_e32 v7, 1.0, v7
	v_div_scale_f32 v8, s[60:61], v7, v7, v21
	v_rcp_f32_e32 v9, v8
	v_div_scale_f32 v10, vcc, v21, v7, v21
	v_fma_f32 v11, -v8, v9, 1.0
	v_fmac_f32_e32 v9, v11, v9
	v_mul_f32_e32 v11, v10, v9
	v_fma_f32 v12, -v8, v11, v10
	v_fmac_f32_e32 v11, v12, v9
	v_fma_f32 v8, -v8, v11, v10
	v_div_fmas_f32 v8, v8, v9, v11
	v_div_fixup_f32 v6, v8, v7, v21
	ds_write_b32 v4, v6 offset:16384
	s_waitcnt vmcnt(8)
	v_mul_f32_e32 v7, 0xbfb8aa3b, v22
	v_exp_f32_e32 v7, v7
	s_nop 0
	v_add_f32_e32 v7, 1.0, v7
	v_div_scale_f32 v8, s[60:61], v7, v7, v22
	v_rcp_f32_e32 v9, v8
	v_div_scale_f32 v10, vcc, v22, v7, v22
	v_fma_f32 v11, -v8, v9, 1.0
	v_fmac_f32_e32 v9, v11, v9
	v_mul_f32_e32 v11, v10, v9
	v_fma_f32 v12, -v8, v11, v10
	v_fmac_f32_e32 v11, v12, v9
	v_fma_f32 v8, -v8, v11, v10
	v_div_fmas_f32 v8, v8, v9, v11
	v_div_fixup_f32 v6, v8, v7, v22
	ds_write_b32 v4, v6 offset:18432
	s_waitcnt vmcnt(7)
	v_mul_f32_e32 v7, 0xbfb8aa3b, v23
	v_exp_f32_e32 v7, v7
	s_nop 0
	v_add_f32_e32 v7, 1.0, v7
	v_div_scale_f32 v8, s[60:61], v7, v7, v23
	v_rcp_f32_e32 v9, v8
	v_div_scale_f32 v10, vcc, v23, v7, v23
	v_fma_f32 v11, -v8, v9, 1.0
	v_fmac_f32_e32 v9, v11, v9
	v_mul_f32_e32 v11, v10, v9
	v_fma_f32 v12, -v8, v11, v10
	v_fmac_f32_e32 v11, v12, v9
	v_fma_f32 v8, -v8, v11, v10
	v_div_fmas_f32 v8, v8, v9, v11
	v_div_fixup_f32 v6, v8, v7, v23
	ds_write_b32 v4, v6 offset:20480
	s_waitcnt vmcnt(6)
	v_mul_f32_e32 v7, 0xbfb8aa3b, v24
	v_exp_f32_e32 v7, v7
	s_nop 0
	v_add_f32_e32 v7, 1.0, v7
	v_div_scale_f32 v8, s[60:61], v7, v7, v24
	v_rcp_f32_e32 v9, v8
	v_div_scale_f32 v10, vcc, v24, v7, v24
	v_fma_f32 v11, -v8, v9, 1.0
	v_fmac_f32_e32 v9, v11, v9
	v_mul_f32_e32 v11, v10, v9
	v_fma_f32 v12, -v8, v11, v10
	v_fmac_f32_e32 v11, v12, v9
	v_fma_f32 v8, -v8, v11, v10
	v_div_fmas_f32 v8, v8, v9, v11
	v_div_fixup_f32 v6, v8, v7, v24
	ds_write_b32 v4, v6 offset:22528
	s_waitcnt vmcnt(5)
	v_mul_f32_e32 v7, 0xbfb8aa3b, v25
	v_exp_f32_e32 v7, v7
	s_nop 0
	v_add_f32_e32 v7, 1.0, v7
	v_div_scale_f32 v8, s[60:61], v7, v7, v25
	v_rcp_f32_e32 v9, v8
	v_div_scale_f32 v10, vcc, v25, v7, v25
	v_fma_f32 v11, -v8, v9, 1.0
	v_fmac_f32_e32 v9, v11, v9
	v_mul_f32_e32 v11, v10, v9
	v_fma_f32 v12, -v8, v11, v10
	v_fmac_f32_e32 v11, v12, v9
	v_fma_f32 v8, -v8, v11, v10
	v_div_fmas_f32 v8, v8, v9, v11
	v_div_fixup_f32 v6, v8, v7, v25
	ds_write_b32 v4, v6 offset:24576
	s_waitcnt vmcnt(4)
	v_mul_f32_e32 v7, 0xbfb8aa3b, v26
	v_exp_f32_e32 v7, v7
	s_nop 0
	v_add_f32_e32 v7, 1.0, v7
	v_div_scale_f32 v8, s[60:61], v7, v7, v26
	v_rcp_f32_e32 v9, v8
	v_div_scale_f32 v10, vcc, v26, v7, v26
	v_fma_f32 v11, -v8, v9, 1.0
	v_fmac_f32_e32 v9, v11, v9
	v_mul_f32_e32 v11, v10, v9
	v_fma_f32 v12, -v8, v11, v10
	v_fmac_f32_e32 v11, v12, v9
	v_fma_f32 v8, -v8, v11, v10
	v_div_fmas_f32 v8, v8, v9, v11
	v_div_fixup_f32 v6, v8, v7, v26
	ds_write_b32 v4, v6 offset:26624
	s_waitcnt vmcnt(3)
	v_mul_f32_e32 v7, 0xbfb8aa3b, v27
	v_exp_f32_e32 v7, v7
	s_nop 0
	v_add_f32_e32 v7, 1.0, v7
	v_div_scale_f32 v8, s[60:61], v7, v7, v27
	v_rcp_f32_e32 v9, v8
	v_div_scale_f32 v10, vcc, v27, v7, v27
	v_fma_f32 v11, -v8, v9, 1.0
	v_fmac_f32_e32 v9, v11, v9
	v_mul_f32_e32 v11, v10, v9
	v_fma_f32 v12, -v8, v11, v10
	v_fmac_f32_e32 v11, v12, v9
	v_fma_f32 v8, -v8, v11, v10
	v_div_fmas_f32 v8, v8, v9, v11
	v_div_fixup_f32 v6, v8, v7, v27
	ds_write_b32 v4, v6 offset:28672
	s_waitcnt vmcnt(2)
	v_mul_f32_e32 v7, 0xbfb8aa3b, v28
	v_exp_f32_e32 v7, v7
	s_nop 0
	v_add_f32_e32 v7, 1.0, v7
	v_div_scale_f32 v8, s[60:61], v7, v7, v28
	v_rcp_f32_e32 v9, v8
	v_div_scale_f32 v10, vcc, v28, v7, v28
	v_fma_f32 v11, -v8, v9, 1.0
	v_fmac_f32_e32 v9, v11, v9
	v_mul_f32_e32 v11, v10, v9
	v_fma_f32 v12, -v8, v11, v10
	v_fmac_f32_e32 v11, v12, v9
	v_fma_f32 v8, -v8, v11, v10
	v_div_fmas_f32 v8, v8, v9, v11
	v_div_fixup_f32 v6, v8, v7, v28
	ds_write_b32 v4, v6 offset:30720
	s_waitcnt vmcnt(1)
	v_mul_f32_e32 v7, 0xbfb8aa3b, v29
	v_exp_f32_e32 v7, v7
	s_nop 0
	v_add_f32_e32 v7, 1.0, v7
	v_div_scale_f32 v8, s[60:61], v7, v7, v29
	v_rcp_f32_e32 v9, v8
	v_div_scale_f32 v10, vcc, v29, v7, v29
	v_fma_f32 v11, -v8, v9, 1.0
	v_fmac_f32_e32 v9, v11, v9
	v_mul_f32_e32 v11, v10, v9
	v_fma_f32 v12, -v8, v11, v10
	v_fmac_f32_e32 v11, v12, v9
	v_fma_f32 v8, -v8, v11, v10
	v_div_fmas_f32 v8, v8, v9, v11
	v_div_fixup_f32 v6, v8, v7, v29
	ds_write_b32 v4, v6 offset:32768
	s_waitcnt vmcnt(0)
	v_mul_f32_e32 v7, 0xbfb8aa3b, v30
	v_exp_f32_e32 v7, v7
	s_nop 0
	v_add_f32_e32 v7, 1.0, v7
	v_div_scale_f32 v8, s[60:61], v7, v7, v30
	v_rcp_f32_e32 v9, v8
	v_div_scale_f32 v10, vcc, v30, v7, v30
	v_fma_f32 v11, -v8, v9, 1.0
	v_fmac_f32_e32 v9, v11, v9
	v_mul_f32_e32 v11, v10, v9
	v_fma_f32 v12, -v8, v11, v10
	v_fmac_f32_e32 v11, v12, v9
	v_fma_f32 v8, -v8, v11, v10
	v_div_fmas_f32 v8, v8, v9, v11
	v_div_fixup_f32 v6, v8, v7, v30
	ds_write_b32 v4, v6 offset:34816
	s_nop 0
	s_nop 0
	s_nop 0
	s_nop 0
	s_nop 0

; DI void phase_prologue(const Params& p, LAS unsigned char* lds, int tid, int lane, int wave) {
;     ...
;         const float* aw = p.in[4] + (size_t)l * 1024 * NMODC + cgp * 64 + lane;
;         float acc[9];
; #pragma unroll
;         for (int r = 0; r < 9; ++r) acc[r] = 0.f;
;         const int kbase = wave * 128;
; #pragma unroll 32
;         for (int k = 0; k < 128; ++k) { const float w = aw[(size_t)(kbase + k) * NMODC];
; #pragma unroll
;             for (int r = 0; r < 9; ++r) acc[r] += sl[r * 1024 + kbase + k] * w; }
.LBB0_17:
	v_mad_u64_u32 v[250:251], s[14:15], s3, v53, v[60:61]
	s_mov_b32 s98, 0x6000
	s_mov_b32 s99, 0
	global_load_dword v106, v[250:251], off
	v_lshl_add_u64 v[250:251], v[250:251], 0, s[98:99]
	global_load_dword v107, v[250:251], off
	v_lshl_add_u64 v[250:251], v[250:251], 0, s[98:99]
	global_load_dword v108, v[250:251], off
	v_lshl_add_u64 v[250:251], v[250:251], 0, s[98:99]
	global_load_dword v109, v[250:251], off
	v_lshl_add_u64 v[250:251], v[250:251], 0, s[98:99]
	global_load_dword v110, v[250:251], off
	v_lshl_add_u64 v[250:251], v[250:251], 0, s[98:99]
	global_load_dword v111, v[250:251], off
	v_lshl_add_u64 v[250:251], v[250:251], 0, s[98:99]
	global_load_dword v112, v[250:251], off
	v_lshl_add_u64 v[250:251], v[250:251], 0, s[98:99]
	global_load_dword v113, v[250:251], off
	v_lshl_add_u64 v[250:251], v[250:251], 0, s[98:99]
	global_load_dword v114, v[250:251], off
	v_lshl_add_u64 v[250:251], v[250:251], 0, s[98:99]
	global_load_dword v115, v[250:251], off
	v_lshl_add_u64 v[250:251], v[250:251], 0, s[98:99]
	global_load_dword v116, v[250:251], off
	v_lshl_add_u64 v[250:251], v[250:251], 0, s[98:99]
	global_load_dword v117, v[250:251], off
	v_lshl_add_u64 v[250:251], v[250:251], 0, s[98:99]
	global_load_dword v118, v[250:251], off
	v_lshl_add_u64 v[250:251], v[250:251], 0, s[98:99]
	global_load_dword v119, v[250:251], off
	v_lshl_add_u64 v[250:251], v[250:251], 0, s[98:99]
	global_load_dword v120, v[250:251], off
	v_lshl_add_u64 v[250:251], v[250:251], 0, s[98:99]
	global_load_dword v121, v[250:251], off
	v_lshl_add_u64 v[250:251], v[250:251], 0, s[98:99]
	global_load_dword v122, v[250:251], off
	v_lshl_add_u64 v[250:251], v[250:251], 0, s[98:99]
	global_load_dword v123, v[250:251], off
	v_lshl_add_u64 v[250:251], v[250:251], 0, s[98:99]
	global_load_dword v124, v[250:251], off
	v_lshl_add_u64 v[250:251], v[250:251], 0, s[98:99]
	global_load_dword v125, v[250:251], off
	v_lshl_add_u64 v[250:251], v[250:251], 0, s[98:99]
	global_load_dword v126, v[250:251], off
	v_lshl_add_u64 v[250:251], v[250:251], 0, s[98:99]
	global_load_dword v127, v[250:251], off
	v_lshl_add_u64 v[250:251], v[250:251], 0, s[98:99]
	global_load_dword v128, v[250:251], off
	v_lshl_add_u64 v[250:251], v[250:251], 0, s[98:99]
	global_load_dword v129, v[250:251], off
	v_lshl_add_u64 v[250:251], v[250:251], 0, s[98:99]
	global_load_dword v130, v[250:251], off
	v_lshl_add_u64 v[250:251], v[250:251], 0, s[98:99]
	global_load_dword v131, v[250:251], off
	v_lshl_add_u64 v[250:251], v[250:251], 0, s[98:99]
	global_load_dword v132, v[250:251], off
	v_lshl_add_u64 v[250:251], v[250:251], 0, s[98:99]
	global_load_dword v133, v[250:251], off
	v_lshl_add_u64 v[250:251], v[250:251], 0, s[98:99]
	global_load_dword v134, v[250:251], off
	v_lshl_add_u64 v[250:251], v[250:251], 0, s[98:99]
	global_load_dword v135, v[250:251], off
	v_lshl_add_u64 v[250:251], v[250:251], 0, s[98:99]
	global_load_dword v136, v[250:251], off
	v_lshl_add_u64 v[250:251], v[250:251], 0, s[98:99]
	global_load_dword v137, v[250:251], off
	v_lshl_add_u64 v[250:251], v[250:251], 0, s[98:99]
	global_load_dword v138, v[250:251], off
	v_lshl_add_u64 v[250:251], v[250:251], 0, s[98:99]
	global_load_dword v139, v[250:251], off
	v_lshl_add_u64 v[250:251], v[250:251], 0, s[98:99]
	global_load_dword v140, v[250:251], off
	v_lshl_add_u64 v[250:251], v[250:251], 0, s[98:99]
	global_load_dword v141, v[250:251], off
	v_lshl_add_u64 v[250:251], v[250:251], 0, s[98:99]
	global_load_dword v142, v[250:251], off
	v_lshl_add_u64 v[250:251], v[250:251], 0, s[98:99]
	global_load_dword v143, v[250:251], off
	v_lshl_add_u64 v[250:251], v[250:251], 0, s[98:99]
	global_load_dword v144, v[250:251], off
	v_lshl_add_u64 v[250:251], v[250:251], 0, s[98:99]
	global_load_dword v145, v[250:251], off
	v_lshl_add_u64 v[250:251], v[250:251], 0, s[98:99]
	global_load_dword v146, v[250:251], off
	v_lshl_add_u64 v[250:251], v[250:251], 0, s[98:99]
	global_load_dword v147, v[250:251], off
	v_lshl_add_u64 v[250:251], v[250:251], 0, s[98:99]
	global_load_dword v148, v[250:251], off
	v_lshl_add_u64 v[250:251], v[250:251], 0, s[98:99]
	global_load_dword v149, v[250:251], off
	v_lshl_add_u64 v[250:251], v[250:251], 0, s[98:99]
	global_load_dword v150, v[250:251], off
	v_lshl_add_u64 v[250:251], v[250:251], 0, s[98:99]
	global_load_dword v151, v[250:251], off
	v_lshl_add_u64 v[250:251], v[250:251], 0, s[98:99]
	global_load_dword v152, v[250:251], off
	v_lshl_add_u64 v[250:251], v[250:251], 0, s[98:99]
	global_load_dword v153, v[250:251], off
	v_lshl_add_u64 v[250:251], v[250:251], 0, s[98:99]
	global_load_dword v154, v[250:251], off
	v_lshl_add_u64 v[250:251], v[250:251], 0, s[98:99]
	global_load_dword v155, v[250:251], off
	v_lshl_add_u64 v[250:251], v[250:251], 0, s[98:99]
	global_load_dword v156, v[250:251], off
	v_lshl_add_u64 v[250:251], v[250:251], 0, s[98:99]
	global_load_dword v157, v[250:251], off
	v_lshl_add_u64 v[250:251], v[250:251], 0, s[98:99]
	global_load_dword v158, v[250:251], off
	v_lshl_add_u64 v[250:251], v[250:251], 0, s[98:99]
	global_load_dword v159, v[250:251], off
	v_lshl_add_u64 v[250:251], v[250:251], 0, s[98:99]
	global_load_dword v160, v[250:251], off
	v_lshl_add_u64 v[250:251], v[250:251], 0, s[98:99]
	global_load_dword v162, v[250:251], off
	v_lshl_add_u64 v[250:251], v[250:251], 0, s[98:99]
	s_mov_b32 s14, s33
	v_mov_b32_e32 v249, s14
	ds_read_b128 v[2:5], v249
	ds_read_b128 v[6:9], v249 offset:16
	ds_read_b128 v[10:13], v249 offset:4096
	ds_read_b128 v[14:17], v249 offset:4112
	ds_read_b128 v[18:21], v249 offset:8192
	ds_read_b128 v[22:25], v249 offset:8208
	ds_read_b128 v[26:29], v249 offset:12288
	ds_read_b128 v[30:33], v249 offset:12304
	ds_read_b128 v[34:37], v249 offset:16384
	ds_read_b128 v[38:41], v249 offset:16400
	ds_read_b128 v[42:45], v249 offset:20480
	ds_read_b128 v[46:49], v249 offset:20496
	ds_read_b128 v[68:71], v249 offset:24576
	ds_read_b128 v[72:75], v249 offset:24592
	ds_read_b128 v[76:79], v249 offset:28672
	ds_read_b128 v[84:87], v249 offset:28688
	ds_read_b128 v[88:91], v249 offset:32768
	ds_read_b128 v[96:99], v249 offset:32784
	s_waitcnt vmcnt(48) lgkmcnt(0)
; DI void phase_prologue(const Params& p, LAS unsigned char* lds, int tid, int lane, int wave) {
;     ...
; #pragma unroll 32
;         for (int k = 0; k < 128; ++k) { const float w = aw[(size_t)(kbase + k) * NMODC];
; #pragma unroll
;             for (int r = 0; r < 9; ++r) acc[r] += sl[r * 1024 + kbase + k] * w; }
	v_fmac_f32_e32 v82, v106, v2
	v_fmac_f32_e32 v83, v106, v10
	v_fmac_f32_e32 v66, v106, v18
	v_fmac_f32_e32 v67, v106, v26
	v_fmac_f32_e32 v64, v106, v34
	v_fmac_f32_e32 v65, v106, v42
	v_fmac_f32_e32 v62, v106, v68
	v_fmac_f32_e32 v63, v106, v76
	v_fmac_f32_e32 v93, v106, v88
	v_fmac_f32_e32 v82, v107, v3
	v_fmac_f32_e32 v83, v107, v11
	v_fmac_f32_e32 v66, v107, v19
	v_fmac_f32_e32 v67, v107, v27
	v_fmac_f32_e32 v64, v107, v35
	v_fmac_f32_e32 v65, v107, v43
	v_fmac_f32_e32 v62, v107, v69
	v_fmac_f32_e32 v63, v107, v77
	v_fmac_f32_e32 v93, v107, v89
	v_fmac_f32_e32 v82, v108, v4
	v_fmac_f32_e32 v83, v108, v12
	v_fmac_f32_e32 v66, v108, v20
	v_fmac_f32_e32 v67, v108, v28
	v_fmac_f32_e32 v64, v108, v36
	v_fmac_f32_e32 v65, v108, v44
	v_fmac_f32_e32 v62, v108, v70
	v_fmac_f32_e32 v63, v108, v78
	v_fmac_f32_e32 v93, v108, v90
	v_fmac_f32_e32 v82, v109, v5
	v_fmac_f32_e32 v83, v109, v13
	v_fmac_f32_e32 v66, v109, v21
	v_fmac_f32_e32 v67, v109, v29
	v_fmac_f32_e32 v64, v109, v37
	v_fmac_f32_e32 v65, v109, v45
	v_fmac_f32_e32 v62, v109, v71
	v_fmac_f32_e32 v63, v109, v79
	v_fmac_f32_e32 v93, v109, v91
	v_fmac_f32_e32 v82, v110, v6
	v_fmac_f32_e32 v83, v110, v14
	v_fmac_f32_e32 v66, v110, v22
	v_fmac_f32_e32 v67, v110, v30
	v_fmac_f32_e32 v64, v110, v38
	v_fmac_f32_e32 v65, v110, v46
	v_fmac_f32_e32 v62, v110, v72
	v_fmac_f32_e32 v63, v110, v84
	v_fmac_f32_e32 v93, v110, v96
	v_fmac_f32_e32 v82, v111, v7
	v_fmac_f32_e32 v83, v111, v15
	v_fmac_f32_e32 v66, v111, v23
	v_fmac_f32_e32 v67, v111, v31
	v_fmac_f32_e32 v64, v111, v39
	v_fmac_f32_e32 v65, v111, v47
	v_fmac_f32_e32 v62, v111, v73
	v_fmac_f32_e32 v63, v111, v85
	v_fmac_f32_e32 v93, v111, v97
	v_fmac_f32_e32 v82, v112, v8
	v_fmac_f32_e32 v83, v112, v16
	v_fmac_f32_e32 v66, v112, v24
	v_fmac_f32_e32 v67, v112, v32
	v_fmac_f32_e32 v64, v112, v40
	v_fmac_f32_e32 v65, v112, v48
	v_fmac_f32_e32 v62, v112, v74
	v_fmac_f32_e32 v63, v112, v86
	v_fmac_f32_e32 v93, v112, v98
	v_fmac_f32_e32 v82, v113, v9
	v_fmac_f32_e32 v83, v113, v17
	v_fmac_f32_e32 v66, v113, v25
	v_fmac_f32_e32 v67, v113, v33
	v_fmac_f32_e32 v64, v113, v41
	v_fmac_f32_e32 v65, v113, v49
	v_fmac_f32_e32 v62, v113, v75
	v_fmac_f32_e32 v63, v113, v87
	v_fmac_f32_e32 v93, v113, v99
	global_load_dword v163, v[250:251], off
	v_lshl_add_u64 v[250:251], v[250:251], 0, s[98:99]
	global_load_dword v164, v[250:251], off
	v_lshl_add_u64 v[250:251], v[250:251], 0, s[98:99]
	global_load_dword v165, v[250:251], off
	v_lshl_add_u64 v[250:251], v[250:251], 0, s[98:99]
	global_load_dword v166, v[250:251], off
	v_lshl_add_u64 v[250:251], v[250:251], 0, s[98:99]
	global_load_dword v167, v[250:251], off
	v_lshl_add_u64 v[250:251], v[250:251], 0, s[98:99]
	global_load_dword v168, v[250:251], off
	v_lshl_add_u64 v[250:251], v[250:251], 0, s[98:99]
	global_load_dword v169, v[250:251], off
	v_lshl_add_u64 v[250:251], v[250:251], 0, s[98:99]
	global_load_dword v170, v[250:251], off
	v_lshl_add_u64 v[250:251], v[250:251], 0, s[98:99]
	s_add_i32 s14, s33, 32
	v_mov_b32_e32 v249, s14
	ds_read_b128 v[2:5], v249
	ds_read_b128 v[6:9], v249 offset:16
	ds_read_b128 v[10:13], v249 offset:4096
	ds_read_b128 v[14:17], v249 offset:4112
	ds_read_b128 v[18:21], v249 offset:8192
	ds_read_b128 v[22:25], v249 offset:8208
	ds_read_b128 v[26:29], v249 offset:12288
	ds_read_b128 v[30:33], v249 offset:12304
	ds_read_b128 v[34:37], v249 offset:16384
	ds_read_b128 v[38:41], v249 offset:16400
	ds_read_b128 v[42:45], v249 offset:20480
	ds_read_b128 v[46:49], v249 offset:20496
	ds_read_b128 v[68:71], v249 offset:24576
	ds_read_b128 v[72:75], v249 offset:24592
	ds_read_b128 v[76:79], v249 offset:28672
	ds_read_b128 v[84:87], v249 offset:28688
	ds_read_b128 v[88:91], v249 offset:32768
	ds_read_b128 v[96:99], v249 offset:32784
	s_waitcnt vmcnt(48) lgkmcnt(0)
	v_fmac_f32_e32 v82, v114, v2
	v_fmac_f32_e32 v83, v114, v10
	v_fmac_f32_e32 v66, v114, v18
	v_fmac_f32_e32 v67, v114, v26
	v_fmac_f32_e32 v64, v114, v34
	v_fmac_f32_e32 v65, v114, v42
	v_fmac_f32_e32 v62, v114, v68
	v_fmac_f32_e32 v63, v114, v76
	v_fmac_f32_e32 v93, v114, v88
	v_fmac_f32_e32 v82, v115, v3
	v_fmac_f32_e32 v83, v115, v11
	v_fmac_f32_e32 v66, v115, v19
	v_fmac_f32_e32 v67, v115, v27
	v_fmac_f32_e32 v64, v115, v35
	v_fmac_f32_e32 v65, v115, v43
	v_fmac_f32_e32 v62, v115, v69
	v_fmac_f32_e32 v63, v115, v77
	v_fmac_f32_e32 v93, v115, v89
	v_fmac_f32_e32 v82, v116, v4
	v_fmac_f32_e32 v83, v116, v12
	v_fmac_f32_e32 v66, v116, v20
	v_fmac_f32_e32 v67, v116, v28
	v_fmac_f32_e32 v64, v116, v36
	v_fmac_f32_e32 v65, v116, v44
	v_fmac_f32_e32 v62, v116, v70
	v_fmac_f32_e32 v63, v116, v78
	v_fmac_f32_e32 v93, v116, v90
	v_fmac_f32_e32 v82, v117, v5
	v_fmac_f32_e32 v83, v117, v13
	v_fmac_f32_e32 v66, v117, v21
	v_fmac_f32_e32 v67, v117, v29
	v_fmac_f32_e32 v64, v117, v37
	v_fmac_f32_e32 v65, v117, v45
	v_fmac_f32_e32 v62, v117, v71
	v_fmac_f32_e32 v63, v117, v79
	v_fmac_f32_e32 v93, v117, v91
	v_fmac_f32_e32 v82, v118, v6
	v_fmac_f32_e32 v83, v118, v14
	v_fmac_f32_e32 v66, v118, v22
	v_fmac_f32_e32 v67, v118, v30
	v_fmac_f32_e32 v64, v118, v38
	v_fmac_f32_e32 v65, v118, v46
	v_fmac_f32_e32 v62, v118, v72
	v_fmac_f32_e32 v63, v118, v84
	v_fmac_f32_e32 v93, v118, v96
	v_fmac_f32_e32 v82, v119, v7
	v_fmac_f32_e32 v83, v119, v15
	v_fmac_f32_e32 v66, v119, v23
	v_fmac_f32_e32 v67, v119, v31
	v_fmac_f32_e32 v64, v119, v39
	v_fmac_f32_e32 v65, v119, v47
	v_fmac_f32_e32 v62, v119, v73
	v_fmac_f32_e32 v63, v119, v85
	v_fmac_f32_e32 v93, v119, v97
	v_fmac_f32_e32 v82, v120, v8
	v_fmac_f32_e32 v83, v120, v16
	v_fmac_f32_e32 v66, v120, v24
	v_fmac_f32_e32 v67, v120, v32
	v_fmac_f32_e32 v64, v120, v40
	v_fmac_f32_e32 v65, v120, v48
; DI void phase_prologue(const Params& p, LAS unsigned char* lds, int tid, int lane, int wave) {
;     ...
; #pragma unroll 32
;         for (int k = 0; k < 128; ++k) { const float w = aw[(size_t)(kbase + k) * NMODC];
; #pragma unroll
;             for (int r = 0; r < 9; ++r) acc[r] += sl[r * 1024 + kbase + k] * w; }
	v_fmac_f32_e32 v62, v120, v74
	v_fmac_f32_e32 v63, v120, v86
	v_fmac_f32_e32 v93, v120, v98
	v_fmac_f32_e32 v82, v121, v9
	v_fmac_f32_e32 v83, v121, v17
	v_fmac_f32_e32 v66, v121, v25
	v_fmac_f32_e32 v67, v121, v33
	v_fmac_f32_e32 v64, v121, v41
	v_fmac_f32_e32 v65, v121, v49
	v_fmac_f32_e32 v62, v121, v75
	v_fmac_f32_e32 v63, v121, v87
	v_fmac_f32_e32 v93, v121, v99
	global_load_dword v171, v[250:251], off
	v_lshl_add_u64 v[250:251], v[250:251], 0, s[98:99]
	global_load_dword v172, v[250:251], off
	v_lshl_add_u64 v[250:251], v[250:251], 0, s[98:99]
	global_load_dword v173, v[250:251], off
	v_lshl_add_u64 v[250:251], v[250:251], 0, s[98:99]
	global_load_dword v174, v[250:251], off
	v_lshl_add_u64 v[250:251], v[250:251], 0, s[98:99]
	global_load_dword v175, v[250:251], off
	v_lshl_add_u64 v[250:251], v[250:251], 0, s[98:99]
	global_load_dword v176, v[250:251], off
	v_lshl_add_u64 v[250:251], v[250:251], 0, s[98:99]
	global_load_dword v177, v[250:251], off
	v_lshl_add_u64 v[250:251], v[250:251], 0, s[98:99]
	global_load_dword v178, v[250:251], off
	v_lshl_add_u64 v[250:251], v[250:251], 0, s[98:99]
	s_add_i32 s14, s33, 64
	v_mov_b32_e32 v249, s14
	ds_read_b128 v[2:5], v249
	ds_read_b128 v[6:9], v249 offset:16
	ds_read_b128 v[10:13], v249 offset:4096
	ds_read_b128 v[14:17], v249 offset:4112
	ds_read_b128 v[18:21], v249 offset:8192
	ds_read_b128 v[22:25], v249 offset:8208
	ds_read_b128 v[26:29], v249 offset:12288
	ds_read_b128 v[30:33], v249 offset:12304
	ds_read_b128 v[34:37], v249 offset:16384
	ds_read_b128 v[38:41], v249 offset:16400
	ds_read_b128 v[42:45], v249 offset:20480
	ds_read_b128 v[46:49], v249 offset:20496
	ds_read_b128 v[68:71], v249 offset:24576
	ds_read_b128 v[72:75], v249 offset:24592
	ds_read_b128 v[76:79], v249 offset:28672
	ds_read_b128 v[84:87], v249 offset:28688
	ds_read_b128 v[88:91], v249 offset:32768
	ds_read_b128 v[96:99], v249 offset:32784
	s_waitcnt vmcnt(48) lgkmcnt(0)
	v_fmac_f32_e32 v82, v122, v2
	v_fmac_f32_e32 v83, v122, v10
	v_fmac_f32_e32 v66, v122, v18
	v_fmac_f32_e32 v67, v122, v26
	v_fmac_f32_e32 v64, v122, v34
	v_fmac_f32_e32 v65, v122, v42
	v_fmac_f32_e32 v62, v122, v68
	v_fmac_f32_e32 v63, v122, v76
	v_fmac_f32_e32 v93, v122, v88
	v_fmac_f32_e32 v82, v123, v3
	v_fmac_f32_e32 v83, v123, v11
	v_fmac_f32_e32 v66, v123, v19
	v_fmac_f32_e32 v67, v123, v27
	v_fmac_f32_e32 v64, v123, v35
	v_fmac_f32_e32 v65, v123, v43
	v_fmac_f32_e32 v62, v123, v69
	v_fmac_f32_e32 v63, v123, v77
	v_fmac_f32_e32 v93, v123, v89
	v_fmac_f32_e32 v82, v124, v4
	v_fmac_f32_e32 v83, v124, v12
	v_fmac_f32_e32 v66, v124, v20
	v_fmac_f32_e32 v67, v124, v28
	v_fmac_f32_e32 v64, v124, v36
	v_fmac_f32_e32 v65, v124, v44
	v_fmac_f32_e32 v62, v124, v70
	v_fmac_f32_e32 v63, v124, v78
	v_fmac_f32_e32 v93, v124, v90
	v_fmac_f32_e32 v82, v125, v5
	v_fmac_f32_e32 v83, v125, v13
	v_fmac_f32_e32 v66, v125, v21
	v_fmac_f32_e32 v67, v125, v29
	v_fmac_f32_e32 v64, v125, v37
	v_fmac_f32_e32 v65, v125, v45
	v_fmac_f32_e32 v62, v125, v71
	v_fmac_f32_e32 v63, v125, v79
	v_fmac_f32_e32 v93, v125, v91
	v_fmac_f32_e32 v82, v126, v6
	v_fmac_f32_e32 v83, v126, v14
	v_fmac_f32_e32 v66, v126, v22
	v_fmac_f32_e32 v67, v126, v30
	v_fmac_f32_e32 v64, v126, v38
	v_fmac_f32_e32 v65, v126, v46
	v_fmac_f32_e32 v62, v126, v72
	v_fmac_f32_e32 v63, v126, v84
	v_fmac_f32_e32 v93, v126, v96
	v_fmac_f32_e32 v82, v127, v7
	v_fmac_f32_e32 v83, v127, v15
	v_fmac_f32_e32 v66, v127, v23
	v_fmac_f32_e32 v67, v127, v31
	v_fmac_f32_e32 v64, v127, v39
	v_fmac_f32_e32 v65, v127, v47
	v_fmac_f32_e32 v62, v127, v73
	v_fmac_f32_e32 v63, v127, v85
	v_fmac_f32_e32 v93, v127, v97
	v_fmac_f32_e32 v82, v128, v8
	v_fmac_f32_e32 v83, v128, v16
	v_fmac_f32_e32 v66, v128, v24
	v_fmac_f32_e32 v67, v128, v32
	v_fmac_f32_e32 v64, v128, v40
	v_fmac_f32_e32 v65, v128, v48
	v_fmac_f32_e32 v62, v128, v74
	v_fmac_f32_e32 v63, v128, v86
	v_fmac_f32_e32 v93, v128, v98
	v_fmac_f32_e32 v82, v129, v9
	v_fmac_f32_e32 v83, v129, v17
	v_fmac_f32_e32 v66, v129, v25
	v_fmac_f32_e32 v67, v129, v33
	v_fmac_f32_e32 v64, v129, v41
	v_fmac_f32_e32 v65, v129, v49
	v_fmac_f32_e32 v62, v129, v75
	v_fmac_f32_e32 v63, v129, v87
	v_fmac_f32_e32 v93, v129, v99
	global_load_dword v179, v[250:251], off
	v_lshl_add_u64 v[250:251], v[250:251], 0, s[98:99]
	global_load_dword v180, v[250:251], off
	v_lshl_add_u64 v[250:251], v[250:251], 0, s[98:99]
	global_load_dword v181, v[250:251], off
	v_lshl_add_u64 v[250:251], v[250:251], 0, s[98:99]
	global_load_dword v182, v[250:251], off
	v_lshl_add_u64 v[250:251], v[250:251], 0, s[98:99]
	global_load_dword v183, v[250:251], off
	v_lshl_add_u64 v[250:251], v[250:251], 0, s[98:99]
	global_load_dword v184, v[250:251], off
	v_lshl_add_u64 v[250:251], v[250:251], 0, s[98:99]
	global_load_dword v185, v[250:251], off
	v_lshl_add_u64 v[250:251], v[250:251], 0, s[98:99]
	global_load_dword v186, v[250:251], off
	v_lshl_add_u64 v[250:251], v[250:251], 0, s[98:99]
	s_add_i32 s14, s33, 96
	v_mov_b32_e32 v249, s14
	ds_read_b128 v[2:5], v249
	ds_read_b128 v[6:9], v249 offset:16
	ds_read_b128 v[10:13], v249 offset:4096
	ds_read_b128 v[14:17], v249 offset:4112
	ds_read_b128 v[18:21], v249 offset:8192
	ds_read_b128 v[22:25], v249 offset:8208
	ds_read_b128 v[26:29], v249 offset:12288
	ds_read_b128 v[30:33], v249 offset:12304
	ds_read_b128 v[34:37], v249 offset:16384
	ds_read_b128 v[38:41], v249 offset:16400
	ds_read_b128 v[42:45], v249 offset:20480
	ds_read_b128 v[46:49], v249 offset:20496
	ds_read_b128 v[68:71], v249 offset:24576
	ds_read_b128 v[72:75], v249 offset:24592
	ds_read_b128 v[76:79], v249 offset:28672
	ds_read_b128 v[84:87], v249 offset:28688
	ds_read_b128 v[88:91], v249 offset:32768
	ds_read_b128 v[96:99], v249 offset:32784
	s_waitcnt vmcnt(48) lgkmcnt(0)
; DI void phase_prologue(const Params& p, LAS unsigned char* lds, int tid, int lane, int wave) {
;     ...
; #pragma unroll 32
;         for (int k = 0; k < 128; ++k) { const float w = aw[(size_t)(kbase + k) * NMODC];
; #pragma unroll
;             for (int r = 0; r < 9; ++r) acc[r] += sl[r * 1024 + kbase + k] * w; }
	v_fmac_f32_e32 v82, v130, v2
	v_fmac_f32_e32 v83, v130, v10
	v_fmac_f32_e32 v66, v130, v18
	v_fmac_f32_e32 v67, v130, v26
	v_fmac_f32_e32 v64, v130, v34
	v_fmac_f32_e32 v65, v130, v42
	v_fmac_f32_e32 v62, v130, v68
	v_fmac_f32_e32 v63, v130, v76
	v_fmac_f32_e32 v93, v130, v88
	v_fmac_f32_e32 v82, v131, v3
	v_fmac_f32_e32 v83, v131, v11
	v_fmac_f32_e32 v66, v131, v19
	v_fmac_f32_e32 v67, v131, v27
	v_fmac_f32_e32 v64, v131, v35
	v_fmac_f32_e32 v65, v131, v43
	v_fmac_f32_e32 v62, v131, v69
	v_fmac_f32_e32 v63, v131, v77
	v_fmac_f32_e32 v93, v131, v89
	v_fmac_f32_e32 v82, v132, v4
	v_fmac_f32_e32 v83, v132, v12
	v_fmac_f32_e32 v66, v132, v20
	v_fmac_f32_e32 v67, v132, v28
	v_fmac_f32_e32 v64, v132, v36
	v_fmac_f32_e32 v65, v132, v44
	v_fmac_f32_e32 v62, v132, v70
	v_fmac_f32_e32 v63, v132, v78
	v_fmac_f32_e32 v93, v132, v90
	v_fmac_f32_e32 v82, v133, v5
	v_fmac_f32_e32 v83, v133, v13
	v_fmac_f32_e32 v66, v133, v21
	v_fmac_f32_e32 v67, v133, v29
	v_fmac_f32_e32 v64, v133, v37
	v_fmac_f32_e32 v65, v133, v45
	v_fmac_f32_e32 v62, v133, v71
	v_fmac_f32_e32 v63, v133, v79
	v_fmac_f32_e32 v93, v133, v91
	v_fmac_f32_e32 v82, v134, v6
	v_fmac_f32_e32 v83, v134, v14
	v_fmac_f32_e32 v66, v134, v22
	v_fmac_f32_e32 v67, v134, v30
	v_fmac_f32_e32 v64, v134, v38
	v_fmac_f32_e32 v65, v134, v46
	v_fmac_f32_e32 v62, v134, v72
	v_fmac_f32_e32 v63, v134, v84
	v_fmac_f32_e32 v93, v134, v96
	v_fmac_f32_e32 v82, v135, v7
	v_fmac_f32_e32 v83, v135, v15
	v_fmac_f32_e32 v66, v135, v23
	v_fmac_f32_e32 v67, v135, v31
	v_fmac_f32_e32 v64, v135, v39
	v_fmac_f32_e32 v65, v135, v47
	v_fmac_f32_e32 v62, v135, v73
	v_fmac_f32_e32 v63, v135, v85
	v_fmac_f32_e32 v93, v135, v97
	v_fmac_f32_e32 v82, v136, v8
	v_fmac_f32_e32 v83, v136, v16
	v_fmac_f32_e32 v66, v136, v24
	v_fmac_f32_e32 v67, v136, v32
	v_fmac_f32_e32 v64, v136, v40
	v_fmac_f32_e32 v65, v136, v48
	v_fmac_f32_e32 v62, v136, v74
	v_fmac_f32_e32 v63, v136, v86
	v_fmac_f32_e32 v93, v136, v98
	v_fmac_f32_e32 v82, v137, v9
	v_fmac_f32_e32 v83, v137, v17
	v_fmac_f32_e32 v66, v137, v25
	v_fmac_f32_e32 v67, v137, v33
	v_fmac_f32_e32 v64, v137, v41
	v_fmac_f32_e32 v65, v137, v49
	v_fmac_f32_e32 v62, v137, v75
	v_fmac_f32_e32 v63, v137, v87
	v_fmac_f32_e32 v93, v137, v99
	global_load_dword v187, v[250:251], off
	v_lshl_add_u64 v[250:251], v[250:251], 0, s[98:99]
	global_load_dword v188, v[250:251], off
	v_lshl_add_u64 v[250:251], v[250:251], 0, s[98:99]
	global_load_dword v189, v[250:251], off
	v_lshl_add_u64 v[250:251], v[250:251], 0, s[98:99]
	global_load_dword v190, v[250:251], off
	v_lshl_add_u64 v[250:251], v[250:251], 0, s[98:99]
	global_load_dword v191, v[250:251], off
	v_lshl_add_u64 v[250:251], v[250:251], 0, s[98:99]
	global_load_dword v192, v[250:251], off
	v_lshl_add_u64 v[250:251], v[250:251], 0, s[98:99]
	global_load_dword v193, v[250:251], off
	v_lshl_add_u64 v[250:251], v[250:251], 0, s[98:99]
	global_load_dword v194, v[250:251], off
	v_lshl_add_u64 v[250:251], v[250:251], 0, s[98:99]
	s_add_i32 s14, s33, 128
	v_mov_b32_e32 v249, s14
	ds_read_b128 v[2:5], v249
	ds_read_b128 v[6:9], v249 offset:16
	ds_read_b128 v[10:13], v249 offset:4096
	ds_read_b128 v[14:17], v249 offset:4112
	ds_read_b128 v[18:21], v249 offset:8192
	ds_read_b128 v[22:25], v249 offset:8208
	ds_read_b128 v[26:29], v249 offset:12288
	ds_read_b128 v[30:33], v249 offset:12304
	ds_read_b128 v[34:37], v249 offset:16384
	ds_read_b128 v[38:41], v249 offset:16400
	ds_read_b128 v[42:45], v249 offset:20480
	ds_read_b128 v[46:49], v249 offset:20496
	ds_read_b128 v[68:71], v249 offset:24576
	ds_read_b128 v[72:75], v249 offset:24592
	ds_read_b128 v[76:79], v249 offset:28672
	ds_read_b128 v[84:87], v249 offset:28688
	ds_read_b128 v[88:91], v249 offset:32768
	ds_read_b128 v[96:99], v249 offset:32784
	s_waitcnt vmcnt(48) lgkmcnt(0)
	v_fmac_f32_e32 v82, v138, v2
	v_fmac_f32_e32 v83, v138, v10
	v_fmac_f32_e32 v66, v138, v18
	v_fmac_f32_e32 v67, v138, v26
	v_fmac_f32_e32 v64, v138, v34
	v_fmac_f32_e32 v65, v138, v42
	v_fmac_f32_e32 v62, v138, v68
	v_fmac_f32_e32 v63, v138, v76
	v_fmac_f32_e32 v93, v138, v88
	v_fmac_f32_e32 v82, v139, v3
	v_fmac_f32_e32 v83, v139, v11
	v_fmac_f32_e32 v66, v139, v19
	v_fmac_f32_e32 v67, v139, v27
	v_fmac_f32_e32 v64, v139, v35
	v_fmac_f32_e32 v65, v139, v43
	v_fmac_f32_e32 v62, v139, v69
	v_fmac_f32_e32 v63, v139, v77
	v_fmac_f32_e32 v93, v139, v89
	v_fmac_f32_e32 v82, v140, v4
	v_fmac_f32_e32 v83, v140, v12
	v_fmac_f32_e32 v66, v140, v20
	v_fmac_f32_e32 v67, v140, v28
	v_fmac_f32_e32 v64, v140, v36
	v_fmac_f32_e32 v65, v140, v44
	v_fmac_f32_e32 v62, v140, v70
	v_fmac_f32_e32 v63, v140, v78
	v_fmac_f32_e32 v93, v140, v90
	v_fmac_f32_e32 v82, v141, v5
	v_fmac_f32_e32 v83, v141, v13
	v_fmac_f32_e32 v66, v141, v21
	v_fmac_f32_e32 v67, v141, v29
	v_fmac_f32_e32 v64, v141, v37
	v_fmac_f32_e32 v65, v141, v45
	v_fmac_f32_e32 v62, v141, v71
	v_fmac_f32_e32 v63, v141, v79
	v_fmac_f32_e32 v93, v141, v91
	v_fmac_f32_e32 v82, v142, v6
	v_fmac_f32_e32 v83, v142, v14
	v_fmac_f32_e32 v66, v142, v22
	v_fmac_f32_e32 v67, v142, v30
	v_fmac_f32_e32 v64, v142, v38
	v_fmac_f32_e32 v65, v142, v46
	v_fmac_f32_e32 v62, v142, v72
	v_fmac_f32_e32 v63, v142, v84
	v_fmac_f32_e32 v93, v142, v96
	v_fmac_f32_e32 v82, v143, v7
	v_fmac_f32_e32 v83, v143, v15
	v_fmac_f32_e32 v66, v143, v23
	v_fmac_f32_e32 v67, v143, v31
	v_fmac_f32_e32 v64, v143, v39
	v_fmac_f32_e32 v65, v143, v47
	v_fmac_f32_e32 v62, v143, v73
	v_fmac_f32_e32 v63, v143, v85
	v_fmac_f32_e32 v93, v143, v97
	v_fmac_f32_e32 v82, v144, v8
	v_fmac_f32_e32 v83, v144, v16
	v_fmac_f32_e32 v66, v144, v24
	v_fmac_f32_e32 v67, v144, v32
	v_fmac_f32_e32 v64, v144, v40
	v_fmac_f32_e32 v65, v144, v48
; DI void phase_prologue(const Params& p, LAS unsigned char* lds, int tid, int lane, int wave) {
;     ...
; #pragma unroll 32
;         for (int k = 0; k < 128; ++k) { const float w = aw[(size_t)(kbase + k) * NMODC];
; #pragma unroll
;             for (int r = 0; r < 9; ++r) acc[r] += sl[r * 1024 + kbase + k] * w; }
	v_fmac_f32_e32 v62, v144, v74
	v_fmac_f32_e32 v63, v144, v86
	v_fmac_f32_e32 v93, v144, v98
	v_fmac_f32_e32 v82, v145, v9
	v_fmac_f32_e32 v83, v145, v17
	v_fmac_f32_e32 v66, v145, v25
	v_fmac_f32_e32 v67, v145, v33
	v_fmac_f32_e32 v64, v145, v41
	v_fmac_f32_e32 v65, v145, v49
	v_fmac_f32_e32 v62, v145, v75
	v_fmac_f32_e32 v63, v145, v87
	v_fmac_f32_e32 v93, v145, v99
	global_load_dword v195, v[250:251], off
	v_lshl_add_u64 v[250:251], v[250:251], 0, s[98:99]
	global_load_dword v196, v[250:251], off
	v_lshl_add_u64 v[250:251], v[250:251], 0, s[98:99]
	global_load_dword v197, v[250:251], off
	v_lshl_add_u64 v[250:251], v[250:251], 0, s[98:99]
	global_load_dword v198, v[250:251], off
	v_lshl_add_u64 v[250:251], v[250:251], 0, s[98:99]
	global_load_dword v199, v[250:251], off
	v_lshl_add_u64 v[250:251], v[250:251], 0, s[98:99]
	global_load_dword v200, v[250:251], off
	v_lshl_add_u64 v[250:251], v[250:251], 0, s[98:99]
	global_load_dword v201, v[250:251], off
	v_lshl_add_u64 v[250:251], v[250:251], 0, s[98:99]
	global_load_dword v202, v[250:251], off
	v_lshl_add_u64 v[250:251], v[250:251], 0, s[98:99]
	s_add_i32 s14, s33, 160
	v_mov_b32_e32 v249, s14
	ds_read_b128 v[2:5], v249
	ds_read_b128 v[6:9], v249 offset:16
	ds_read_b128 v[10:13], v249 offset:4096
	ds_read_b128 v[14:17], v249 offset:4112
	ds_read_b128 v[18:21], v249 offset:8192
	ds_read_b128 v[22:25], v249 offset:8208
	ds_read_b128 v[26:29], v249 offset:12288
	ds_read_b128 v[30:33], v249 offset:12304
	ds_read_b128 v[34:37], v249 offset:16384
	ds_read_b128 v[38:41], v249 offset:16400
	ds_read_b128 v[42:45], v249 offset:20480
	ds_read_b128 v[46:49], v249 offset:20496
	ds_read_b128 v[68:71], v249 offset:24576
	ds_read_b128 v[72:75], v249 offset:24592
	ds_read_b128 v[76:79], v249 offset:28672
	ds_read_b128 v[84:87], v249 offset:28688
	ds_read_b128 v[88:91], v249 offset:32768
	ds_read_b128 v[96:99], v249 offset:32784
	s_waitcnt vmcnt(48) lgkmcnt(0)
	v_fmac_f32_e32 v82, v146, v2
	v_fmac_f32_e32 v83, v146, v10
	v_fmac_f32_e32 v66, v146, v18
	v_fmac_f32_e32 v67, v146, v26
	v_fmac_f32_e32 v64, v146, v34
	v_fmac_f32_e32 v65, v146, v42
	v_fmac_f32_e32 v62, v146, v68
	v_fmac_f32_e32 v63, v146, v76
	v_fmac_f32_e32 v93, v146, v88
	v_fmac_f32_e32 v82, v147, v3
	v_fmac_f32_e32 v83, v147, v11
	v_fmac_f32_e32 v66, v147, v19
	v_fmac_f32_e32 v67, v147, v27
	v_fmac_f32_e32 v64, v147, v35
	v_fmac_f32_e32 v65, v147, v43
	v_fmac_f32_e32 v62, v147, v69
	v_fmac_f32_e32 v63, v147, v77
	v_fmac_f32_e32 v93, v147, v89
	v_fmac_f32_e32 v82, v148, v4
	v_fmac_f32_e32 v83, v148, v12
	v_fmac_f32_e32 v66, v148, v20
	v_fmac_f32_e32 v67, v148, v28
	v_fmac_f32_e32 v64, v148, v36
	v_fmac_f32_e32 v65, v148, v44
	v_fmac_f32_e32 v62, v148, v70
	v_fmac_f32_e32 v63, v148, v78
	v_fmac_f32_e32 v93, v148, v90
	v_fmac_f32_e32 v82, v149, v5
	v_fmac_f32_e32 v83, v149, v13
	v_fmac_f32_e32 v66, v149, v21
	v_fmac_f32_e32 v67, v149, v29
	v_fmac_f32_e32 v64, v149, v37
	v_fmac_f32_e32 v65, v149, v45
	v_fmac_f32_e32 v62, v149, v71
	v_fmac_f32_e32 v63, v149, v79
	v_fmac_f32_e32 v93, v149, v91
	v_fmac_f32_e32 v82, v150, v6
	v_fmac_f32_e32 v83, v150, v14
	v_fmac_f32_e32 v66, v150, v22
	v_fmac_f32_e32 v67, v150, v30
	v_fmac_f32_e32 v64, v150, v38
	v_fmac_f32_e32 v65, v150, v46
	v_fmac_f32_e32 v62, v150, v72
	v_fmac_f32_e32 v63, v150, v84
	v_fmac_f32_e32 v93, v150, v96
	v_fmac_f32_e32 v82, v151, v7
	v_fmac_f32_e32 v83, v151, v15
	v_fmac_f32_e32 v66, v151, v23
	v_fmac_f32_e32 v67, v151, v31
	v_fmac_f32_e32 v64, v151, v39
	v_fmac_f32_e32 v65, v151, v47
	v_fmac_f32_e32 v62, v151, v73
	v_fmac_f32_e32 v63, v151, v85
	v_fmac_f32_e32 v93, v151, v97
	v_fmac_f32_e32 v82, v152, v8
	v_fmac_f32_e32 v83, v152, v16
	v_fmac_f32_e32 v66, v152, v24
	v_fmac_f32_e32 v67, v152, v32
	v_fmac_f32_e32 v64, v152, v40
	v_fmac_f32_e32 v65, v152, v48
	v_fmac_f32_e32 v62, v152, v74
	v_fmac_f32_e32 v63, v152, v86
	v_fmac_f32_e32 v93, v152, v98
	v_fmac_f32_e32 v82, v153, v9
	v_fmac_f32_e32 v83, v153, v17
	v_fmac_f32_e32 v66, v153, v25
	v_fmac_f32_e32 v67, v153, v33
	v_fmac_f32_e32 v64, v153, v41
	v_fmac_f32_e32 v65, v153, v49
	v_fmac_f32_e32 v62, v153, v75
	v_fmac_f32_e32 v63, v153, v87
	v_fmac_f32_e32 v93, v153, v99
	global_load_dword v203, v[250:251], off
	v_lshl_add_u64 v[250:251], v[250:251], 0, s[98:99]
	global_load_dword v204, v[250:251], off
	v_lshl_add_u64 v[250:251], v[250:251], 0, s[98:99]
	global_load_dword v205, v[250:251], off
	v_lshl_add_u64 v[250:251], v[250:251], 0, s[98:99]
	global_load_dword v206, v[250:251], off
	v_lshl_add_u64 v[250:251], v[250:251], 0, s[98:99]
	global_load_dword v207, v[250:251], off
	v_lshl_add_u64 v[250:251], v[250:251], 0, s[98:99]
	global_load_dword v208, v[250:251], off
	v_lshl_add_u64 v[250:251], v[250:251], 0, s[98:99]
	global_load_dword v209, v[250:251], off
	v_lshl_add_u64 v[250:251], v[250:251], 0, s[98:99]
	global_load_dword v210, v[250:251], off
	v_lshl_add_u64 v[250:251], v[250:251], 0, s[98:99]
	s_add_i32 s14, s33, 192
	v_mov_b32_e32 v249, s14
	ds_read_b128 v[2:5], v249
	ds_read_b128 v[6:9], v249 offset:16
	ds_read_b128 v[10:13], v249 offset:4096
	ds_read_b128 v[14:17], v249 offset:4112
	ds_read_b128 v[18:21], v249 offset:8192
	ds_read_b128 v[22:25], v249 offset:8208
	ds_read_b128 v[26:29], v249 offset:12288
	ds_read_b128 v[30:33], v249 offset:12304
	ds_read_b128 v[34:37], v249 offset:16384
	ds_read_b128 v[38:41], v249 offset:16400
	ds_read_b128 v[42:45], v249 offset:20480
	ds_read_b128 v[46:49], v249 offset:20496
	ds_read_b128 v[68:71], v249 offset:24576
	ds_read_b128 v[72:75], v249 offset:24592
	ds_read_b128 v[76:79], v249 offset:28672
	ds_read_b128 v[84:87], v249 offset:28688
	ds_read_b128 v[88:91], v249 offset:32768
	ds_read_b128 v[96:99], v249 offset:32784
	s_waitcnt vmcnt(48) lgkmcnt(0)
; DI void phase_prologue(const Params& p, LAS unsigned char* lds, int tid, int lane, int wave) {
;     ...
; #pragma unroll 32
;         for (int k = 0; k < 128; ++k) { const float w = aw[(size_t)(kbase + k) * NMODC];
; #pragma unroll
;             for (int r = 0; r < 9; ++r) acc[r] += sl[r * 1024 + kbase + k] * w; }
	v_fmac_f32_e32 v82, v154, v2
	v_fmac_f32_e32 v83, v154, v10
	v_fmac_f32_e32 v66, v154, v18
	v_fmac_f32_e32 v67, v154, v26
	v_fmac_f32_e32 v64, v154, v34
	v_fmac_f32_e32 v65, v154, v42
	v_fmac_f32_e32 v62, v154, v68
	v_fmac_f32_e32 v63, v154, v76
	v_fmac_f32_e32 v93, v154, v88
	v_fmac_f32_e32 v82, v155, v3
	v_fmac_f32_e32 v83, v155, v11
	v_fmac_f32_e32 v66, v155, v19
	v_fmac_f32_e32 v67, v155, v27
	v_fmac_f32_e32 v64, v155, v35
	v_fmac_f32_e32 v65, v155, v43
	v_fmac_f32_e32 v62, v155, v69
	v_fmac_f32_e32 v63, v155, v77
	v_fmac_f32_e32 v93, v155, v89
	v_fmac_f32_e32 v82, v156, v4
	v_fmac_f32_e32 v83, v156, v12
	v_fmac_f32_e32 v66, v156, v20
	v_fmac_f32_e32 v67, v156, v28
	v_fmac_f32_e32 v64, v156, v36
	v_fmac_f32_e32 v65, v156, v44
	v_fmac_f32_e32 v62, v156, v70
	v_fmac_f32_e32 v63, v156, v78
	v_fmac_f32_e32 v93, v156, v90
	v_fmac_f32_e32 v82, v157, v5
	v_fmac_f32_e32 v83, v157, v13
	v_fmac_f32_e32 v66, v157, v21
	v_fmac_f32_e32 v67, v157, v29
	v_fmac_f32_e32 v64, v157, v37
	v_fmac_f32_e32 v65, v157, v45
	v_fmac_f32_e32 v62, v157, v71
	v_fmac_f32_e32 v63, v157, v79
	v_fmac_f32_e32 v93, v157, v91
	v_fmac_f32_e32 v82, v158, v6
	v_fmac_f32_e32 v83, v158, v14
	v_fmac_f32_e32 v66, v158, v22
	v_fmac_f32_e32 v67, v158, v30
	v_fmac_f32_e32 v64, v158, v38
	v_fmac_f32_e32 v65, v158, v46
	v_fmac_f32_e32 v62, v158, v72
	v_fmac_f32_e32 v63, v158, v84
	v_fmac_f32_e32 v93, v158, v96
	v_fmac_f32_e32 v82, v159, v7
	v_fmac_f32_e32 v83, v159, v15
	v_fmac_f32_e32 v66, v159, v23
	v_fmac_f32_e32 v67, v159, v31
	v_fmac_f32_e32 v64, v159, v39
	v_fmac_f32_e32 v65, v159, v47
	v_fmac_f32_e32 v62, v159, v73
	v_fmac_f32_e32 v63, v159, v85
	v_fmac_f32_e32 v93, v159, v97
	v_fmac_f32_e32 v82, v160, v8
	v_fmac_f32_e32 v83, v160, v16
	v_fmac_f32_e32 v66, v160, v24
	v_fmac_f32_e32 v67, v160, v32
	v_fmac_f32_e32 v64, v160, v40
	v_fmac_f32_e32 v65, v160, v48
	v_fmac_f32_e32 v62, v160, v74
	v_fmac_f32_e32 v63, v160, v86
	v_fmac_f32_e32 v93, v160, v98
	v_fmac_f32_e32 v82, v162, v9
	v_fmac_f32_e32 v83, v162, v17
	v_fmac_f32_e32 v66, v162, v25
	v_fmac_f32_e32 v67, v162, v33
	v_fmac_f32_e32 v64, v162, v41
	v_fmac_f32_e32 v65, v162, v49
	v_fmac_f32_e32 v62, v162, v75
	v_fmac_f32_e32 v63, v162, v87
	v_fmac_f32_e32 v93, v162, v99
	global_load_dword v211, v[250:251], off
	v_lshl_add_u64 v[250:251], v[250:251], 0, s[98:99]
	global_load_dword v212, v[250:251], off
	v_lshl_add_u64 v[250:251], v[250:251], 0, s[98:99]
	global_load_dword v213, v[250:251], off
	v_lshl_add_u64 v[250:251], v[250:251], 0, s[98:99]
	global_load_dword v214, v[250:251], off
	v_lshl_add_u64 v[250:251], v[250:251], 0, s[98:99]
	global_load_dword v215, v[250:251], off
	v_lshl_add_u64 v[250:251], v[250:251], 0, s[98:99]
	global_load_dword v216, v[250:251], off
	v_lshl_add_u64 v[250:251], v[250:251], 0, s[98:99]
	global_load_dword v217, v[250:251], off
	v_lshl_add_u64 v[250:251], v[250:251], 0, s[98:99]
	global_load_dword v218, v[250:251], off
	v_lshl_add_u64 v[250:251], v[250:251], 0, s[98:99]
	s_add_i32 s14, s33, 224
	v_mov_b32_e32 v249, s14
	ds_read_b128 v[2:5], v249
	ds_read_b128 v[6:9], v249 offset:16
	ds_read_b128 v[10:13], v249 offset:4096
	ds_read_b128 v[14:17], v249 offset:4112
	ds_read_b128 v[18:21], v249 offset:8192
	ds_read_b128 v[22:25], v249 offset:8208
	ds_read_b128 v[26:29], v249 offset:12288
	ds_read_b128 v[30:33], v249 offset:12304
	ds_read_b128 v[34:37], v249 offset:16384
	ds_read_b128 v[38:41], v249 offset:16400
	ds_read_b128 v[42:45], v249 offset:20480
	ds_read_b128 v[46:49], v249 offset:20496
	ds_read_b128 v[68:71], v249 offset:24576
	ds_read_b128 v[72:75], v249 offset:24592
	ds_read_b128 v[76:79], v249 offset:28672
	ds_read_b128 v[84:87], v249 offset:28688
	ds_read_b128 v[88:91], v249 offset:32768
	ds_read_b128 v[96:99], v249 offset:32784
	s_waitcnt vmcnt(48) lgkmcnt(0)
	v_fmac_f32_e32 v82, v163, v2
	v_fmac_f32_e32 v83, v163, v10
	v_fmac_f32_e32 v66, v163, v18
	v_fmac_f32_e32 v67, v163, v26
	v_fmac_f32_e32 v64, v163, v34
	v_fmac_f32_e32 v65, v163, v42
	v_fmac_f32_e32 v62, v163, v68
	v_fmac_f32_e32 v63, v163, v76
	v_fmac_f32_e32 v93, v163, v88
	v_fmac_f32_e32 v82, v164, v3
	v_fmac_f32_e32 v83, v164, v11
	v_fmac_f32_e32 v66, v164, v19
	v_fmac_f32_e32 v67, v164, v27
	v_fmac_f32_e32 v64, v164, v35
	v_fmac_f32_e32 v65, v164, v43
	v_fmac_f32_e32 v62, v164, v69
	v_fmac_f32_e32 v63, v164, v77
	v_fmac_f32_e32 v93, v164, v89
	v_fmac_f32_e32 v82, v165, v4
	v_fmac_f32_e32 v83, v165, v12
	v_fmac_f32_e32 v66, v165, v20
	v_fmac_f32_e32 v67, v165, v28
	v_fmac_f32_e32 v64, v165, v36
	v_fmac_f32_e32 v65, v165, v44
	v_fmac_f32_e32 v62, v165, v70
	v_fmac_f32_e32 v63, v165, v78
	v_fmac_f32_e32 v93, v165, v90
	v_fmac_f32_e32 v82, v166, v5
	v_fmac_f32_e32 v83, v166, v13
	v_fmac_f32_e32 v66, v166, v21
	v_fmac_f32_e32 v67, v166, v29
	v_fmac_f32_e32 v64, v166, v37
	v_fmac_f32_e32 v65, v166, v45
	v_fmac_f32_e32 v62, v166, v71
	v_fmac_f32_e32 v63, v166, v79
	v_fmac_f32_e32 v93, v166, v91
	v_fmac_f32_e32 v82, v167, v6
	v_fmac_f32_e32 v83, v167, v14
	v_fmac_f32_e32 v66, v167, v22
	v_fmac_f32_e32 v67, v167, v30
	v_fmac_f32_e32 v64, v167, v38
	v_fmac_f32_e32 v65, v167, v46
	v_fmac_f32_e32 v62, v167, v72
	v_fmac_f32_e32 v63, v167, v84
	v_fmac_f32_e32 v93, v167, v96
	v_fmac_f32_e32 v82, v168, v7
	v_fmac_f32_e32 v83, v168, v15
	v_fmac_f32_e32 v66, v168, v23
	v_fmac_f32_e32 v67, v168, v31
	v_fmac_f32_e32 v64, v168, v39
	v_fmac_f32_e32 v65, v168, v47
	v_fmac_f32_e32 v62, v168, v73
	v_fmac_f32_e32 v63, v168, v85
	v_fmac_f32_e32 v93, v168, v97
	v_fmac_f32_e32 v82, v169, v8
	v_fmac_f32_e32 v83, v169, v16
	v_fmac_f32_e32 v66, v169, v24
	v_fmac_f32_e32 v67, v169, v32
	v_fmac_f32_e32 v64, v169, v40
	v_fmac_f32_e32 v65, v169, v48
; DI void phase_prologue(const Params& p, LAS unsigned char* lds, int tid, int lane, int wave) {
;     ...
; #pragma unroll 32
;         for (int k = 0; k < 128; ++k) { const float w = aw[(size_t)(kbase + k) * NMODC];
; #pragma unroll
;             for (int r = 0; r < 9; ++r) acc[r] += sl[r * 1024 + kbase + k] * w; }
	v_fmac_f32_e32 v62, v169, v74
	v_fmac_f32_e32 v63, v169, v86
	v_fmac_f32_e32 v93, v169, v98
	v_fmac_f32_e32 v82, v170, v9
	v_fmac_f32_e32 v83, v170, v17
	v_fmac_f32_e32 v66, v170, v25
	v_fmac_f32_e32 v67, v170, v33
	v_fmac_f32_e32 v64, v170, v41
	v_fmac_f32_e32 v65, v170, v49
	v_fmac_f32_e32 v62, v170, v75
	v_fmac_f32_e32 v63, v170, v87
	v_fmac_f32_e32 v93, v170, v99
	global_load_dword v219, v[250:251], off
	v_lshl_add_u64 v[250:251], v[250:251], 0, s[98:99]
	global_load_dword v220, v[250:251], off
	v_lshl_add_u64 v[250:251], v[250:251], 0, s[98:99]
	global_load_dword v221, v[250:251], off
	v_lshl_add_u64 v[250:251], v[250:251], 0, s[98:99]
	global_load_dword v222, v[250:251], off
	v_lshl_add_u64 v[250:251], v[250:251], 0, s[98:99]
	global_load_dword v223, v[250:251], off
	v_lshl_add_u64 v[250:251], v[250:251], 0, s[98:99]
	global_load_dword v224, v[250:251], off
	v_lshl_add_u64 v[250:251], v[250:251], 0, s[98:99]
	global_load_dword v225, v[250:251], off
	v_lshl_add_u64 v[250:251], v[250:251], 0, s[98:99]
	global_load_dword v226, v[250:251], off
	v_lshl_add_u64 v[250:251], v[250:251], 0, s[98:99]
	s_add_i32 s14, s33, 256
	v_mov_b32_e32 v249, s14
	ds_read_b128 v[2:5], v249
	ds_read_b128 v[6:9], v249 offset:16
	ds_read_b128 v[10:13], v249 offset:4096
	ds_read_b128 v[14:17], v249 offset:4112
	ds_read_b128 v[18:21], v249 offset:8192
	ds_read_b128 v[22:25], v249 offset:8208
	ds_read_b128 v[26:29], v249 offset:12288
	ds_read_b128 v[30:33], v249 offset:12304
	ds_read_b128 v[34:37], v249 offset:16384
	ds_read_b128 v[38:41], v249 offset:16400
	ds_read_b128 v[42:45], v249 offset:20480
	ds_read_b128 v[46:49], v249 offset:20496
	ds_read_b128 v[68:71], v249 offset:24576
	ds_read_b128 v[72:75], v249 offset:24592
	ds_read_b128 v[76:79], v249 offset:28672
	ds_read_b128 v[84:87], v249 offset:28688
	ds_read_b128 v[88:91], v249 offset:32768
	ds_read_b128 v[96:99], v249 offset:32784
	s_waitcnt vmcnt(48) lgkmcnt(0)
	v_fmac_f32_e32 v82, v171, v2
	v_fmac_f32_e32 v83, v171, v10
	v_fmac_f32_e32 v66, v171, v18
	v_fmac_f32_e32 v67, v171, v26
	v_fmac_f32_e32 v64, v171, v34
	v_fmac_f32_e32 v65, v171, v42
	v_fmac_f32_e32 v62, v171, v68
	v_fmac_f32_e32 v63, v171, v76
	v_fmac_f32_e32 v93, v171, v88
	v_fmac_f32_e32 v82, v172, v3
	v_fmac_f32_e32 v83, v172, v11
	v_fmac_f32_e32 v66, v172, v19
	v_fmac_f32_e32 v67, v172, v27
	v_fmac_f32_e32 v64, v172, v35
	v_fmac_f32_e32 v65, v172, v43
	v_fmac_f32_e32 v62, v172, v69
	v_fmac_f32_e32 v63, v172, v77
	v_fmac_f32_e32 v93, v172, v89
	v_fmac_f32_e32 v82, v173, v4
	v_fmac_f32_e32 v83, v173, v12
	v_fmac_f32_e32 v66, v173, v20
	v_fmac_f32_e32 v67, v173, v28
	v_fmac_f32_e32 v64, v173, v36
	v_fmac_f32_e32 v65, v173, v44
	v_fmac_f32_e32 v62, v173, v70
	v_fmac_f32_e32 v63, v173, v78
	v_fmac_f32_e32 v93, v173, v90
	v_fmac_f32_e32 v82, v174, v5
	v_fmac_f32_e32 v83, v174, v13
	v_fmac_f32_e32 v66, v174, v21
	v_fmac_f32_e32 v67, v174, v29
	v_fmac_f32_e32 v64, v174, v37
	v_fmac_f32_e32 v65, v174, v45
	v_fmac_f32_e32 v62, v174, v71
	v_fmac_f32_e32 v63, v174, v79
	v_fmac_f32_e32 v93, v174, v91
	v_fmac_f32_e32 v82, v175, v6
	v_fmac_f32_e32 v83, v175, v14
	v_fmac_f32_e32 v66, v175, v22
	v_fmac_f32_e32 v67, v175, v30
	v_fmac_f32_e32 v64, v175, v38
	v_fmac_f32_e32 v65, v175, v46
	v_fmac_f32_e32 v62, v175, v72
	v_fmac_f32_e32 v63, v175, v84
	v_fmac_f32_e32 v93, v175, v96
	v_fmac_f32_e32 v82, v176, v7
	v_fmac_f32_e32 v83, v176, v15
	v_fmac_f32_e32 v66, v176, v23
	v_fmac_f32_e32 v67, v176, v31
	v_fmac_f32_e32 v64, v176, v39
	v_fmac_f32_e32 v65, v176, v47
	v_fmac_f32_e32 v62, v176, v73
	v_fmac_f32_e32 v63, v176, v85
	v_fmac_f32_e32 v93, v176, v97
	v_fmac_f32_e32 v82, v177, v8
	v_fmac_f32_e32 v83, v177, v16
	v_fmac_f32_e32 v66, v177, v24
	v_fmac_f32_e32 v67, v177, v32
	v_fmac_f32_e32 v64, v177, v40
	v_fmac_f32_e32 v65, v177, v48
	v_fmac_f32_e32 v62, v177, v74
	v_fmac_f32_e32 v63, v177, v86
	v_fmac_f32_e32 v93, v177, v98
	v_fmac_f32_e32 v82, v178, v9
	v_fmac_f32_e32 v83, v178, v17
	v_fmac_f32_e32 v66, v178, v25
	v_fmac_f32_e32 v67, v178, v33
	v_fmac_f32_e32 v64, v178, v41
	v_fmac_f32_e32 v65, v178, v49
	v_fmac_f32_e32 v62, v178, v75
	v_fmac_f32_e32 v63, v178, v87
	v_fmac_f32_e32 v93, v178, v99
	global_load_dword v227, v[250:251], off
	v_lshl_add_u64 v[250:251], v[250:251], 0, s[98:99]
	global_load_dword v228, v[250:251], off
	v_lshl_add_u64 v[250:251], v[250:251], 0, s[98:99]
	global_load_dword v229, v[250:251], off
	v_lshl_add_u64 v[250:251], v[250:251], 0, s[98:99]
	global_load_dword v230, v[250:251], off
	v_lshl_add_u64 v[250:251], v[250:251], 0, s[98:99]
	global_load_dword v231, v[250:251], off
	v_lshl_add_u64 v[250:251], v[250:251], 0, s[98:99]
	global_load_dword v232, v[250:251], off
	v_lshl_add_u64 v[250:251], v[250:251], 0, s[98:99]
	global_load_dword v233, v[250:251], off
	v_lshl_add_u64 v[250:251], v[250:251], 0, s[98:99]
	global_load_dword v234, v[250:251], off
	v_lshl_add_u64 v[250:251], v[250:251], 0, s[98:99]
	s_add_i32 s14, s33, 288
	v_mov_b32_e32 v249, s14
	ds_read_b128 v[2:5], v249
	ds_read_b128 v[6:9], v249 offset:16
	ds_read_b128 v[10:13], v249 offset:4096
	ds_read_b128 v[14:17], v249 offset:4112
	ds_read_b128 v[18:21], v249 offset:8192
	ds_read_b128 v[22:25], v249 offset:8208
	ds_read_b128 v[26:29], v249 offset:12288
	ds_read_b128 v[30:33], v249 offset:12304
	ds_read_b128 v[34:37], v249 offset:16384
	ds_read_b128 v[38:41], v249 offset:16400
	ds_read_b128 v[42:45], v249 offset:20480
	ds_read_b128 v[46:49], v249 offset:20496
	ds_read_b128 v[68:71], v249 offset:24576
	ds_read_b128 v[72:75], v249 offset:24592
	ds_read_b128 v[76:79], v249 offset:28672
	ds_read_b128 v[84:87], v249 offset:28688
	ds_read_b128 v[88:91], v249 offset:32768
	ds_read_b128 v[96:99], v249 offset:32784
	s_waitcnt vmcnt(48) lgkmcnt(0)
; DI void phase_prologue(const Params& p, LAS unsigned char* lds, int tid, int lane, int wave) {
;     ...
; #pragma unroll 32
;         for (int k = 0; k < 128; ++k) { const float w = aw[(size_t)(kbase + k) * NMODC];
; #pragma unroll
;             for (int r = 0; r < 9; ++r) acc[r] += sl[r * 1024 + kbase + k] * w; }
	v_fmac_f32_e32 v82, v179, v2
	v_fmac_f32_e32 v83, v179, v10
	v_fmac_f32_e32 v66, v179, v18
	v_fmac_f32_e32 v67, v179, v26
	v_fmac_f32_e32 v64, v179, v34
	v_fmac_f32_e32 v65, v179, v42
	v_fmac_f32_e32 v62, v179, v68
	v_fmac_f32_e32 v63, v179, v76
	v_fmac_f32_e32 v93, v179, v88
	v_fmac_f32_e32 v82, v180, v3
	v_fmac_f32_e32 v83, v180, v11
	v_fmac_f32_e32 v66, v180, v19
	v_fmac_f32_e32 v67, v180, v27
	v_fmac_f32_e32 v64, v180, v35
	v_fmac_f32_e32 v65, v180, v43
	v_fmac_f32_e32 v62, v180, v69
	v_fmac_f32_e32 v63, v180, v77
	v_fmac_f32_e32 v93, v180, v89
	v_fmac_f32_e32 v82, v181, v4
	v_fmac_f32_e32 v83, v181, v12
	v_fmac_f32_e32 v66, v181, v20
	v_fmac_f32_e32 v67, v181, v28
	v_fmac_f32_e32 v64, v181, v36
	v_fmac_f32_e32 v65, v181, v44
	v_fmac_f32_e32 v62, v181, v70
	v_fmac_f32_e32 v63, v181, v78
	v_fmac_f32_e32 v93, v181, v90
	v_fmac_f32_e32 v82, v182, v5
	v_fmac_f32_e32 v83, v182, v13
	v_fmac_f32_e32 v66, v182, v21
	v_fmac_f32_e32 v67, v182, v29
	v_fmac_f32_e32 v64, v182, v37
	v_fmac_f32_e32 v65, v182, v45
	v_fmac_f32_e32 v62, v182, v71
	v_fmac_f32_e32 v63, v182, v79
	v_fmac_f32_e32 v93, v182, v91
	v_fmac_f32_e32 v82, v183, v6
	v_fmac_f32_e32 v83, v183, v14
	v_fmac_f32_e32 v66, v183, v22
	v_fmac_f32_e32 v67, v183, v30
	v_fmac_f32_e32 v64, v183, v38
	v_fmac_f32_e32 v65, v183, v46
	v_fmac_f32_e32 v62, v183, v72
	v_fmac_f32_e32 v63, v183, v84
	v_fmac_f32_e32 v93, v183, v96
	v_fmac_f32_e32 v82, v184, v7
	v_fmac_f32_e32 v83, v184, v15
	v_fmac_f32_e32 v66, v184, v23
	v_fmac_f32_e32 v67, v184, v31
	v_fmac_f32_e32 v64, v184, v39
	v_fmac_f32_e32 v65, v184, v47
	v_fmac_f32_e32 v62, v184, v73
	v_fmac_f32_e32 v63, v184, v85
	v_fmac_f32_e32 v93, v184, v97
	v_fmac_f32_e32 v82, v185, v8
	v_fmac_f32_e32 v83, v185, v16
	v_fmac_f32_e32 v66, v185, v24
	v_fmac_f32_e32 v67, v185, v32
	v_fmac_f32_e32 v64, v185, v40
	v_fmac_f32_e32 v65, v185, v48
	v_fmac_f32_e32 v62, v185, v74
	v_fmac_f32_e32 v63, v185, v86
	v_fmac_f32_e32 v93, v185, v98
	v_fmac_f32_e32 v82, v186, v9
	v_fmac_f32_e32 v83, v186, v17
	v_fmac_f32_e32 v66, v186, v25
	v_fmac_f32_e32 v67, v186, v33
	v_fmac_f32_e32 v64, v186, v41
	v_fmac_f32_e32 v65, v186, v49
	v_fmac_f32_e32 v62, v186, v75
	v_fmac_f32_e32 v63, v186, v87
	v_fmac_f32_e32 v93, v186, v99
	s_add_i32 s14, s33, 320
	v_mov_b32_e32 v249, s14
	ds_read_b128 v[2:5], v249
	ds_read_b128 v[6:9], v249 offset:16
	ds_read_b128 v[10:13], v249 offset:4096
	ds_read_b128 v[14:17], v249 offset:4112
	ds_read_b128 v[18:21], v249 offset:8192
	ds_read_b128 v[22:25], v249 offset:8208
	ds_read_b128 v[26:29], v249 offset:12288
	ds_read_b128 v[30:33], v249 offset:12304
	ds_read_b128 v[34:37], v249 offset:16384
	ds_read_b128 v[38:41], v249 offset:16400
	ds_read_b128 v[42:45], v249 offset:20480
	ds_read_b128 v[46:49], v249 offset:20496
	ds_read_b128 v[68:71], v249 offset:24576
	ds_read_b128 v[72:75], v249 offset:24592
	ds_read_b128 v[76:79], v249 offset:28672
	ds_read_b128 v[84:87], v249 offset:28688
	ds_read_b128 v[88:91], v249 offset:32768
	ds_read_b128 v[96:99], v249 offset:32784
	s_waitcnt vmcnt(40) lgkmcnt(0)
	v_fmac_f32_e32 v82, v187, v2
	v_fmac_f32_e32 v83, v187, v10
	v_fmac_f32_e32 v66, v187, v18
	v_fmac_f32_e32 v67, v187, v26
	v_fmac_f32_e32 v64, v187, v34
	v_fmac_f32_e32 v65, v187, v42
	v_fmac_f32_e32 v62, v187, v68
	v_fmac_f32_e32 v63, v187, v76
	v_fmac_f32_e32 v93, v187, v88
	v_fmac_f32_e32 v82, v188, v3
	v_fmac_f32_e32 v83, v188, v11
	v_fmac_f32_e32 v66, v188, v19
	v_fmac_f32_e32 v67, v188, v27
	v_fmac_f32_e32 v64, v188, v35
	v_fmac_f32_e32 v65, v188, v43
	v_fmac_f32_e32 v62, v188, v69
	v_fmac_f32_e32 v63, v188, v77
	v_fmac_f32_e32 v93, v188, v89
	v_fmac_f32_e32 v82, v189, v4
	v_fmac_f32_e32 v83, v189, v12
	v_fmac_f32_e32 v66, v189, v20
	v_fmac_f32_e32 v67, v189, v28
	v_fmac_f32_e32 v64, v189, v36
	v_fmac_f32_e32 v65, v189, v44
	v_fmac_f32_e32 v62, v189, v70
	v_fmac_f32_e32 v63, v189, v78
	v_fmac_f32_e32 v93, v189, v90
	v_fmac_f32_e32 v82, v190, v5
	v_fmac_f32_e32 v83, v190, v13
	v_fmac_f32_e32 v66, v190, v21
	v_fmac_f32_e32 v67, v190, v29
	v_fmac_f32_e32 v64, v190, v37
	v_fmac_f32_e32 v65, v190, v45
	v_fmac_f32_e32 v62, v190, v71
	v_fmac_f32_e32 v63, v190, v79
	v_fmac_f32_e32 v93, v190, v91
	v_fmac_f32_e32 v82, v191, v6
	v_fmac_f32_e32 v83, v191, v14
	v_fmac_f32_e32 v66, v191, v22
	v_fmac_f32_e32 v67, v191, v30
	v_fmac_f32_e32 v64, v191, v38
	v_fmac_f32_e32 v65, v191, v46
	v_fmac_f32_e32 v62, v191, v72
	v_fmac_f32_e32 v63, v191, v84
	v_fmac_f32_e32 v93, v191, v96
	v_fmac_f32_e32 v82, v192, v7
	v_fmac_f32_e32 v83, v192, v15
	v_fmac_f32_e32 v66, v192, v23
	v_fmac_f32_e32 v67, v192, v31
	v_fmac_f32_e32 v64, v192, v39
	v_fmac_f32_e32 v65, v192, v47
	v_fmac_f32_e32 v62, v192, v73
	v_fmac_f32_e32 v63, v192, v85
	v_fmac_f32_e32 v93, v192, v97
	v_fmac_f32_e32 v82, v193, v8
	v_fmac_f32_e32 v83, v193, v16
	v_fmac_f32_e32 v66, v193, v24
	v_fmac_f32_e32 v67, v193, v32
	v_fmac_f32_e32 v64, v193, v40
	v_fmac_f32_e32 v65, v193, v48
	v_fmac_f32_e32 v62, v193, v74
	v_fmac_f32_e32 v63, v193, v86
	v_fmac_f32_e32 v93, v193, v98
	v_fmac_f32_e32 v82, v194, v9
	v_fmac_f32_e32 v83, v194, v17
	v_fmac_f32_e32 v66, v194, v25
	v_fmac_f32_e32 v67, v194, v33
	v_fmac_f32_e32 v64, v194, v41
	v_fmac_f32_e32 v65, v194, v49
	v_fmac_f32_e32 v62, v194, v75
	v_fmac_f32_e32 v63, v194, v87
	v_fmac_f32_e32 v93, v194, v99
	s_add_i32 s14, s33, 352
	v_mov_b32_e32 v249, s14
	ds_read_b128 v[2:5], v249
	ds_read_b128 v[6:9], v249 offset:16
	ds_read_b128 v[10:13], v249 offset:4096
	ds_read_b128 v[14:17], v249 offset:4112
	ds_read_b128 v[18:21], v249 offset:8192
	ds_read_b128 v[22:25], v249 offset:8208
	ds_read_b128 v[26:29], v249 offset:12288
	ds_read_b128 v[30:33], v249 offset:12304
	ds_read_b128 v[34:37], v249 offset:16384
	ds_read_b128 v[38:41], v249 offset:16400
	ds_read_b128 v[42:45], v249 offset:20480
	ds_read_b128 v[46:49], v249 offset:20496
	ds_read_b128 v[68:71], v249 offset:24576
	ds_read_b128 v[72:75], v249 offset:24592
	ds_read_b128 v[76:79], v249 offset:28672
	ds_read_b128 v[84:87], v249 offset:28688
	ds_read_b128 v[88:91], v249 offset:32768
	ds_read_b128 v[96:99], v249 offset:32784
	s_waitcnt vmcnt(32) lgkmcnt(0)
; DI void phase_prologue(const Params& p, LAS unsigned char* lds, int tid, int lane, int wave) {
;     ...
; #pragma unroll 32
;         for (int k = 0; k < 128; ++k) { const float w = aw[(size_t)(kbase + k) * NMODC];
; #pragma unroll
;             for (int r = 0; r < 9; ++r) acc[r] += sl[r * 1024 + kbase + k] * w; }
	v_fmac_f32_e32 v82, v195, v2
	v_fmac_f32_e32 v83, v195, v10
	v_fmac_f32_e32 v66, v195, v18
	v_fmac_f32_e32 v67, v195, v26
	v_fmac_f32_e32 v64, v195, v34
	v_fmac_f32_e32 v65, v195, v42
	v_fmac_f32_e32 v62, v195, v68
	v_fmac_f32_e32 v63, v195, v76
	v_fmac_f32_e32 v93, v195, v88
	v_fmac_f32_e32 v82, v196, v3
	v_fmac_f32_e32 v83, v196, v11
	v_fmac_f32_e32 v66, v196, v19
	v_fmac_f32_e32 v67, v196, v27
	v_fmac_f32_e32 v64, v196, v35
	v_fmac_f32_e32 v65, v196, v43
	v_fmac_f32_e32 v62, v196, v69
	v_fmac_f32_e32 v63, v196, v77
	v_fmac_f32_e32 v93, v196, v89
	v_fmac_f32_e32 v82, v197, v4
	v_fmac_f32_e32 v83, v197, v12
	v_fmac_f32_e32 v66, v197, v20
	v_fmac_f32_e32 v67, v197, v28
	v_fmac_f32_e32 v64, v197, v36
	v_fmac_f32_e32 v65, v197, v44
	v_fmac_f32_e32 v62, v197, v70
	v_fmac_f32_e32 v63, v197, v78
	v_fmac_f32_e32 v93, v197, v90
	v_fmac_f32_e32 v82, v198, v5
	v_fmac_f32_e32 v83, v198, v13
	v_fmac_f32_e32 v66, v198, v21
	v_fmac_f32_e32 v67, v198, v29
	v_fmac_f32_e32 v64, v198, v37
	v_fmac_f32_e32 v65, v198, v45
	v_fmac_f32_e32 v62, v198, v71
	v_fmac_f32_e32 v63, v198, v79
	v_fmac_f32_e32 v93, v198, v91
	v_fmac_f32_e32 v82, v199, v6
	v_fmac_f32_e32 v83, v199, v14
	v_fmac_f32_e32 v66, v199, v22
	v_fmac_f32_e32 v67, v199, v30
	v_fmac_f32_e32 v64, v199, v38
	v_fmac_f32_e32 v65, v199, v46
	v_fmac_f32_e32 v62, v199, v72
	v_fmac_f32_e32 v63, v199, v84
	v_fmac_f32_e32 v93, v199, v96
	v_fmac_f32_e32 v82, v200, v7
	v_fmac_f32_e32 v83, v200, v15
	v_fmac_f32_e32 v66, v200, v23
	v_fmac_f32_e32 v67, v200, v31
	v_fmac_f32_e32 v64, v200, v39
	v_fmac_f32_e32 v65, v200, v47
	v_fmac_f32_e32 v62, v200, v73
	v_fmac_f32_e32 v63, v200, v85
	v_fmac_f32_e32 v93, v200, v97
	v_fmac_f32_e32 v82, v201, v8
	v_fmac_f32_e32 v83, v201, v16
	v_fmac_f32_e32 v66, v201, v24
	v_fmac_f32_e32 v67, v201, v32
	v_fmac_f32_e32 v64, v201, v40
	v_fmac_f32_e32 v65, v201, v48
	v_fmac_f32_e32 v62, v201, v74
	v_fmac_f32_e32 v63, v201, v86
	v_fmac_f32_e32 v93, v201, v98
	v_fmac_f32_e32 v82, v202, v9
	v_fmac_f32_e32 v83, v202, v17
	v_fmac_f32_e32 v66, v202, v25
	v_fmac_f32_e32 v67, v202, v33
	v_fmac_f32_e32 v64, v202, v41
	v_fmac_f32_e32 v65, v202, v49
	v_fmac_f32_e32 v62, v202, v75
	v_fmac_f32_e32 v63, v202, v87
	v_fmac_f32_e32 v93, v202, v99
	s_add_i32 s14, s33, 384
	v_mov_b32_e32 v249, s14
	ds_read_b128 v[2:5], v249
	ds_read_b128 v[6:9], v249 offset:16
	ds_read_b128 v[10:13], v249 offset:4096
	ds_read_b128 v[14:17], v249 offset:4112
	ds_read_b128 v[18:21], v249 offset:8192
	ds_read_b128 v[22:25], v249 offset:8208
	ds_read_b128 v[26:29], v249 offset:12288
	ds_read_b128 v[30:33], v249 offset:12304
	ds_read_b128 v[34:37], v249 offset:16384
	ds_read_b128 v[38:41], v249 offset:16400
	ds_read_b128 v[42:45], v249 offset:20480
	ds_read_b128 v[46:49], v249 offset:20496
	ds_read_b128 v[68:71], v249 offset:24576
	ds_read_b128 v[72:75], v249 offset:24592
	ds_read_b128 v[76:79], v249 offset:28672
	ds_read_b128 v[84:87], v249 offset:28688
	ds_read_b128 v[88:91], v249 offset:32768
	ds_read_b128 v[96:99], v249 offset:32784
	s_waitcnt vmcnt(24) lgkmcnt(0)
	v_fmac_f32_e32 v82, v203, v2
	v_fmac_f32_e32 v83, v203, v10
	v_fmac_f32_e32 v66, v203, v18
	v_fmac_f32_e32 v67, v203, v26
	v_fmac_f32_e32 v64, v203, v34
	v_fmac_f32_e32 v65, v203, v42
	v_fmac_f32_e32 v62, v203, v68
	v_fmac_f32_e32 v63, v203, v76
	v_fmac_f32_e32 v93, v203, v88
	v_fmac_f32_e32 v82, v204, v3
	v_fmac_f32_e32 v83, v204, v11
	v_fmac_f32_e32 v66, v204, v19
	v_fmac_f32_e32 v67, v204, v27
	v_fmac_f32_e32 v64, v204, v35
	v_fmac_f32_e32 v65, v204, v43
	v_fmac_f32_e32 v62, v204, v69
	v_fmac_f32_e32 v63, v204, v77
	v_fmac_f32_e32 v93, v204, v89
	v_fmac_f32_e32 v82, v205, v4
	v_fmac_f32_e32 v83, v205, v12
	v_fmac_f32_e32 v66, v205, v20
	v_fmac_f32_e32 v67, v205, v28
	v_fmac_f32_e32 v64, v205, v36
	v_fmac_f32_e32 v65, v205, v44
	v_fmac_f32_e32 v62, v205, v70
	v_fmac_f32_e32 v63, v205, v78
	v_fmac_f32_e32 v93, v205, v90
	v_fmac_f32_e32 v82, v206, v5
	v_fmac_f32_e32 v83, v206, v13
	v_fmac_f32_e32 v66, v206, v21
	v_fmac_f32_e32 v67, v206, v29
	v_fmac_f32_e32 v64, v206, v37
	v_fmac_f32_e32 v65, v206, v45
	v_fmac_f32_e32 v62, v206, v71
	v_fmac_f32_e32 v63, v206, v79
	v_fmac_f32_e32 v93, v206, v91
	v_fmac_f32_e32 v82, v207, v6
	v_fmac_f32_e32 v83, v207, v14
	v_fmac_f32_e32 v66, v207, v22
	v_fmac_f32_e32 v67, v207, v30
	v_fmac_f32_e32 v64, v207, v38
	v_fmac_f32_e32 v65, v207, v46
	v_fmac_f32_e32 v62, v207, v72
	v_fmac_f32_e32 v63, v207, v84
	v_fmac_f32_e32 v93, v207, v96
	v_fmac_f32_e32 v82, v208, v7
	v_fmac_f32_e32 v83, v208, v15
	v_fmac_f32_e32 v66, v208, v23
	v_fmac_f32_e32 v67, v208, v31
	v_fmac_f32_e32 v64, v208, v39
	v_fmac_f32_e32 v65, v208, v47
	v_fmac_f32_e32 v62, v208, v73
	v_fmac_f32_e32 v63, v208, v85
	v_fmac_f32_e32 v93, v208, v97
	v_fmac_f32_e32 v82, v209, v8
	v_fmac_f32_e32 v83, v209, v16
	v_fmac_f32_e32 v66, v209, v24
	v_fmac_f32_e32 v67, v209, v32
	v_fmac_f32_e32 v64, v209, v40
	v_fmac_f32_e32 v65, v209, v48
	v_fmac_f32_e32 v62, v209, v74
	v_fmac_f32_e32 v63, v209, v86
	v_fmac_f32_e32 v93, v209, v98
	v_fmac_f32_e32 v82, v210, v9
	v_fmac_f32_e32 v83, v210, v17
	v_fmac_f32_e32 v66, v210, v25
	v_fmac_f32_e32 v67, v210, v33
	v_fmac_f32_e32 v64, v210, v41
	v_fmac_f32_e32 v65, v210, v49
	v_fmac_f32_e32 v62, v210, v75
	v_fmac_f32_e32 v63, v210, v87
	v_fmac_f32_e32 v93, v210, v99
	s_add_i32 s14, s33, 416
	v_mov_b32_e32 v249, s14
	ds_read_b128 v[2:5], v249
	ds_read_b128 v[6:9], v249 offset:16
	ds_read_b128 v[10:13], v249 offset:4096
	ds_read_b128 v[14:17], v249 offset:4112
	ds_read_b128 v[18:21], v249 offset:8192
	ds_read_b128 v[22:25], v249 offset:8208
	ds_read_b128 v[26:29], v249 offset:12288
	ds_read_b128 v[30:33], v249 offset:12304
	ds_read_b128 v[34:37], v249 offset:16384
	ds_read_b128 v[38:41], v249 offset:16400
	ds_read_b128 v[42:45], v249 offset:20480
	ds_read_b128 v[46:49], v249 offset:20496
	ds_read_b128 v[68:71], v249 offset:24576
	ds_read_b128 v[72:75], v249 offset:24592
	ds_read_b128 v[76:79], v249 offset:28672
	ds_read_b128 v[84:87], v249 offset:28688
	ds_read_b128 v[88:91], v249 offset:32768
	ds_read_b128 v[96:99], v249 offset:32784
	s_waitcnt vmcnt(16) lgkmcnt(0)
; DI void phase_prologue(const Params& p, LAS unsigned char* lds, int tid, int lane, int wave) {
;     ...
; #pragma unroll 32
;         for (int k = 0; k < 128; ++k) { const float w = aw[(size_t)(kbase + k) * NMODC];
; #pragma unroll
;             for (int r = 0; r < 9; ++r) acc[r] += sl[r * 1024 + kbase + k] * w; }
	v_fmac_f32_e32 v82, v211, v2
	v_fmac_f32_e32 v83, v211, v10
	v_fmac_f32_e32 v66, v211, v18
	v_fmac_f32_e32 v67, v211, v26
	v_fmac_f32_e32 v64, v211, v34
	v_fmac_f32_e32 v65, v211, v42
	v_fmac_f32_e32 v62, v211, v68
	v_fmac_f32_e32 v63, v211, v76
	v_fmac_f32_e32 v93, v211, v88
	v_fmac_f32_e32 v82, v212, v3
	v_fmac_f32_e32 v83, v212, v11
	v_fmac_f32_e32 v66, v212, v19
	v_fmac_f32_e32 v67, v212, v27
	v_fmac_f32_e32 v64, v212, v35
	v_fmac_f32_e32 v65, v212, v43
	v_fmac_f32_e32 v62, v212, v69
	v_fmac_f32_e32 v63, v212, v77
	v_fmac_f32_e32 v93, v212, v89
	v_fmac_f32_e32 v82, v213, v4
	v_fmac_f32_e32 v83, v213, v12
	v_fmac_f32_e32 v66, v213, v20
	v_fmac_f32_e32 v67, v213, v28
	v_fmac_f32_e32 v64, v213, v36
	v_fmac_f32_e32 v65, v213, v44
	v_fmac_f32_e32 v62, v213, v70
	v_fmac_f32_e32 v63, v213, v78
	v_fmac_f32_e32 v93, v213, v90
	v_fmac_f32_e32 v82, v214, v5
	v_fmac_f32_e32 v83, v214, v13
	v_fmac_f32_e32 v66, v214, v21
	v_fmac_f32_e32 v67, v214, v29
	v_fmac_f32_e32 v64, v214, v37
	v_fmac_f32_e32 v65, v214, v45
	v_fmac_f32_e32 v62, v214, v71
	v_fmac_f32_e32 v63, v214, v79
	v_fmac_f32_e32 v93, v214, v91
	v_fmac_f32_e32 v82, v215, v6
	v_fmac_f32_e32 v83, v215, v14
	v_fmac_f32_e32 v66, v215, v22
	v_fmac_f32_e32 v67, v215, v30
	v_fmac_f32_e32 v64, v215, v38
	v_fmac_f32_e32 v65, v215, v46
	v_fmac_f32_e32 v62, v215, v72
	v_fmac_f32_e32 v63, v215, v84
	v_fmac_f32_e32 v93, v215, v96
	v_fmac_f32_e32 v82, v216, v7
	v_fmac_f32_e32 v83, v216, v15
	v_fmac_f32_e32 v66, v216, v23
	v_fmac_f32_e32 v67, v216, v31
	v_fmac_f32_e32 v64, v216, v39
	v_fmac_f32_e32 v65, v216, v47
	v_fmac_f32_e32 v62, v216, v73
	v_fmac_f32_e32 v63, v216, v85
	v_fmac_f32_e32 v93, v216, v97
	v_fmac_f32_e32 v82, v217, v8
	v_fmac_f32_e32 v83, v217, v16
	v_fmac_f32_e32 v66, v217, v24
	v_fmac_f32_e32 v67, v217, v32
	v_fmac_f32_e32 v64, v217, v40
	v_fmac_f32_e32 v65, v217, v48
	v_fmac_f32_e32 v62, v217, v74
	v_fmac_f32_e32 v63, v217, v86
	v_fmac_f32_e32 v93, v217, v98
	v_fmac_f32_e32 v82, v218, v9
	v_fmac_f32_e32 v83, v218, v17
	v_fmac_f32_e32 v66, v218, v25
	v_fmac_f32_e32 v67, v218, v33
	v_fmac_f32_e32 v64, v218, v41
	v_fmac_f32_e32 v65, v218, v49
	v_fmac_f32_e32 v62, v218, v75
	v_fmac_f32_e32 v63, v218, v87
	v_fmac_f32_e32 v93, v218, v99
	s_add_i32 s14, s33, 448
	v_mov_b32_e32 v249, s14
	ds_read_b128 v[2:5], v249
	ds_read_b128 v[6:9], v249 offset:16
	ds_read_b128 v[10:13], v249 offset:4096
	ds_read_b128 v[14:17], v249 offset:4112
	ds_read_b128 v[18:21], v249 offset:8192
	ds_read_b128 v[22:25], v249 offset:8208
	ds_read_b128 v[26:29], v249 offset:12288
	ds_read_b128 v[30:33], v249 offset:12304
	ds_read_b128 v[34:37], v249 offset:16384
	ds_read_b128 v[38:41], v249 offset:16400
	ds_read_b128 v[42:45], v249 offset:20480
	ds_read_b128 v[46:49], v249 offset:20496
	ds_read_b128 v[68:71], v249 offset:24576
	ds_read_b128 v[72:75], v249 offset:24592
	ds_read_b128 v[76:79], v249 offset:28672
	ds_read_b128 v[84:87], v249 offset:28688
	ds_read_b128 v[88:91], v249 offset:32768
	ds_read_b128 v[96:99], v249 offset:32784
	s_waitcnt vmcnt(8) lgkmcnt(0)
; DI void phase_prologue(const Params& p, LAS unsigned char* lds, int tid, int lane, int wave) {
;     ...
; #pragma unroll 32
;         for (int k = 0; k < 128; ++k) { const float w = aw[(size_t)(kbase + k) * NMODC];
; #pragma unroll
;             for (int r = 0; r < 9; ++r) acc[r] += sl[r * 1024 + kbase + k] * w; }
; #pragma unroll
;         for (int r = 0; r < 9; ++r) part[(wave * 9 + r) * 64 + lane] = acc[r];
;         __syncthreads();
;         for (int i = tid; i < 576; i += 512) { const int r = i >> 6, cl = i & 63; float s = p.in[5][l * NMODC + cgp * 64 + cl];
; #pragma unroll
;             for (int kg = 0; kg < 8; ++kg) s += part[(kg * 9 + r) * 64 + cl];
;             MOD[(l * 9 + r) * NMODC + cgp * 64 + cl] = s; }
	v_fmac_f32_e32 v82, v219, v2
	v_fmac_f32_e32 v83, v219, v10
	v_fmac_f32_e32 v66, v219, v18
	v_fmac_f32_e32 v67, v219, v26
	v_fmac_f32_e32 v64, v219, v34
	v_fmac_f32_e32 v65, v219, v42
	v_fmac_f32_e32 v62, v219, v68
	v_fmac_f32_e32 v63, v219, v76
	v_fmac_f32_e32 v93, v219, v88
	v_fmac_f32_e32 v82, v220, v3
	v_fmac_f32_e32 v83, v220, v11
	v_fmac_f32_e32 v66, v220, v19
	v_fmac_f32_e32 v67, v220, v27
	v_fmac_f32_e32 v64, v220, v35
	v_fmac_f32_e32 v65, v220, v43
	v_fmac_f32_e32 v62, v220, v69
	v_fmac_f32_e32 v63, v220, v77
	v_fmac_f32_e32 v93, v220, v89
	v_fmac_f32_e32 v82, v221, v4
	v_fmac_f32_e32 v83, v221, v12
	v_fmac_f32_e32 v66, v221, v20
	v_fmac_f32_e32 v67, v221, v28
	v_fmac_f32_e32 v64, v221, v36
	v_fmac_f32_e32 v65, v221, v44
	v_fmac_f32_e32 v62, v221, v70
	v_fmac_f32_e32 v63, v221, v78
	v_fmac_f32_e32 v93, v221, v90
	v_fmac_f32_e32 v82, v222, v5
	v_fmac_f32_e32 v83, v222, v13
	v_fmac_f32_e32 v66, v222, v21
	v_fmac_f32_e32 v67, v222, v29
	v_fmac_f32_e32 v64, v222, v37
	v_fmac_f32_e32 v65, v222, v45
	v_fmac_f32_e32 v62, v222, v71
	v_fmac_f32_e32 v63, v222, v79
	v_fmac_f32_e32 v93, v222, v91
	v_fmac_f32_e32 v82, v223, v6
	v_fmac_f32_e32 v83, v223, v14
	v_fmac_f32_e32 v66, v223, v22
	v_fmac_f32_e32 v67, v223, v30
	v_fmac_f32_e32 v64, v223, v38
	v_fmac_f32_e32 v65, v223, v46
	v_fmac_f32_e32 v62, v223, v72
	v_fmac_f32_e32 v63, v223, v84
	v_fmac_f32_e32 v93, v223, v96
	v_fmac_f32_e32 v82, v224, v7
	v_fmac_f32_e32 v83, v224, v15
	v_fmac_f32_e32 v66, v224, v23
	v_fmac_f32_e32 v67, v224, v31
	v_fmac_f32_e32 v64, v224, v39
	v_fmac_f32_e32 v65, v224, v47
	v_fmac_f32_e32 v62, v224, v73
	v_fmac_f32_e32 v63, v224, v85
	v_fmac_f32_e32 v93, v224, v97
	v_fmac_f32_e32 v82, v225, v8
	v_fmac_f32_e32 v83, v225, v16
	v_fmac_f32_e32 v66, v225, v24
	v_fmac_f32_e32 v67, v225, v32
	v_fmac_f32_e32 v64, v225, v40
	v_fmac_f32_e32 v65, v225, v48
	v_fmac_f32_e32 v62, v225, v74
	v_fmac_f32_e32 v63, v225, v86
	v_fmac_f32_e32 v93, v225, v98
	v_fmac_f32_e32 v82, v226, v9
	v_fmac_f32_e32 v83, v226, v17
	v_fmac_f32_e32 v66, v226, v25
	v_fmac_f32_e32 v67, v226, v33
	v_fmac_f32_e32 v64, v226, v41
	v_fmac_f32_e32 v65, v226, v49
	v_fmac_f32_e32 v62, v226, v75
	v_fmac_f32_e32 v63, v226, v87
	v_fmac_f32_e32 v93, v226, v99
	s_add_i32 s14, s33, 480
	v_mov_b32_e32 v249, s14
	ds_read_b128 v[2:5], v249
	ds_read_b128 v[6:9], v249 offset:16
	ds_read_b128 v[10:13], v249 offset:4096
	ds_read_b128 v[14:17], v249 offset:4112
	ds_read_b128 v[18:21], v249 offset:8192
	ds_read_b128 v[22:25], v249 offset:8208
	ds_read_b128 v[26:29], v249 offset:12288
	ds_read_b128 v[30:33], v249 offset:12304
	ds_read_b128 v[34:37], v249 offset:16384
	ds_read_b128 v[38:41], v249 offset:16400
	ds_read_b128 v[42:45], v249 offset:20480
	ds_read_b128 v[46:49], v249 offset:20496
	ds_read_b128 v[68:71], v249 offset:24576
	ds_read_b128 v[72:75], v249 offset:24592
	ds_read_b128 v[76:79], v249 offset:28672
	ds_read_b128 v[84:87], v249 offset:28688
	ds_read_b128 v[88:91], v249 offset:32768
	ds_read_b128 v[96:99], v249 offset:32784
	s_waitcnt vmcnt(0) lgkmcnt(0)
	v_fmac_f32_e32 v82, v227, v2
	v_fmac_f32_e32 v83, v227, v10
	v_fmac_f32_e32 v66, v227, v18
	v_fmac_f32_e32 v67, v227, v26
	v_fmac_f32_e32 v64, v227, v34
	v_fmac_f32_e32 v65, v227, v42
	v_fmac_f32_e32 v62, v227, v68
	v_fmac_f32_e32 v63, v227, v76
	v_fmac_f32_e32 v93, v227, v88
	v_fmac_f32_e32 v82, v228, v3
	v_fmac_f32_e32 v83, v228, v11
	v_fmac_f32_e32 v66, v228, v19
	v_fmac_f32_e32 v67, v228, v27
	v_fmac_f32_e32 v64, v228, v35
	v_fmac_f32_e32 v65, v228, v43
	v_fmac_f32_e32 v62, v228, v69
	v_fmac_f32_e32 v63, v228, v77
	v_fmac_f32_e32 v93, v228, v89
	v_fmac_f32_e32 v82, v229, v4
	v_fmac_f32_e32 v83, v229, v12
	v_fmac_f32_e32 v66, v229, v20
	v_fmac_f32_e32 v67, v229, v28
	v_fmac_f32_e32 v64, v229, v36
	v_fmac_f32_e32 v65, v229, v44
	v_fmac_f32_e32 v62, v229, v70
	v_fmac_f32_e32 v63, v229, v78
	v_fmac_f32_e32 v93, v229, v90
	v_fmac_f32_e32 v82, v230, v5
	v_fmac_f32_e32 v83, v230, v13
	v_fmac_f32_e32 v66, v230, v21
	v_fmac_f32_e32 v67, v230, v29
	v_fmac_f32_e32 v64, v230, v37
	v_fmac_f32_e32 v65, v230, v45
	v_fmac_f32_e32 v62, v230, v71
	v_fmac_f32_e32 v63, v230, v79
	v_fmac_f32_e32 v93, v230, v91
	v_fmac_f32_e32 v82, v231, v6
	v_fmac_f32_e32 v83, v231, v14
	v_fmac_f32_e32 v66, v231, v22
	v_fmac_f32_e32 v67, v231, v30
	v_fmac_f32_e32 v64, v231, v38
	v_fmac_f32_e32 v65, v231, v46
	v_fmac_f32_e32 v62, v231, v72
	v_fmac_f32_e32 v63, v231, v84
	v_fmac_f32_e32 v93, v231, v96
	v_fmac_f32_e32 v82, v232, v7
	v_fmac_f32_e32 v83, v232, v15
	v_fmac_f32_e32 v66, v232, v23
	v_fmac_f32_e32 v67, v232, v31
	v_fmac_f32_e32 v64, v232, v39
	v_fmac_f32_e32 v65, v232, v47
	v_fmac_f32_e32 v62, v232, v73
	v_fmac_f32_e32 v63, v232, v85
	v_fmac_f32_e32 v93, v232, v97
	v_fmac_f32_e32 v82, v233, v8
	v_fmac_f32_e32 v83, v233, v16
	v_fmac_f32_e32 v66, v233, v24
	v_fmac_f32_e32 v67, v233, v32
	v_fmac_f32_e32 v64, v233, v40
	v_fmac_f32_e32 v65, v233, v48
	v_fmac_f32_e32 v62, v233, v74
	v_fmac_f32_e32 v63, v233, v86
	v_fmac_f32_e32 v93, v233, v98
	v_fmac_f32_e32 v82, v234, v9
	v_fmac_f32_e32 v83, v234, v17
	v_fmac_f32_e32 v66, v234, v25
	v_fmac_f32_e32 v67, v234, v33
	v_fmac_f32_e32 v64, v234, v41
	v_fmac_f32_e32 v65, v234, v49
	v_fmac_f32_e32 v62, v234, v75
	v_fmac_f32_e32 v63, v234, v87
	v_fmac_f32_e32 v93, v234, v99
	s_nop 0
	s_nop 0
	s_nop 0
	s_nop 0
	s_nop 0
	s_nop 0
	v_add_u32_e32 v2, s16, v51
	ds_write2st64_b32 v2, v82, v83 offset0:144 offset1:145
	ds_write2st64_b32 v2, v66, v67 offset0:146 offset1:147
	ds_write2st64_b32 v2, v64, v65 offset0:148 offset1:149
	ds_write2st64_b32 v2, v62, v63 offset0:150 offset1:151
	ds_write_b32 v2, v93 offset:38912
	s_waitcnt lgkmcnt(0)
	s_barrier
	s_and_saveexec_b64 s[14:15], s[4:5]
	s_cbranch_execz .LBB0_12
	s_load_dwordx16 s[64:79], s[0:1], 0x0
	s_mul_i32 s13, s81, 0x1800
	s_add_i32 s13, s12, s13
	v_or_b32_e32 v2, s13, v50
	v_ashrrev_i32_e32 v3, 31, v2
	s_mul_i32 s81, s81, 9
	s_waitcnt lgkmcnt(0)
	v_lshl_add_u64 v[2:3], v[2:3], 2, s[74:75]
	v_or_b32_e32 v4, s12, v50
	s_mov_b64 s[12:13], 0
	v_mov_b32_e32 v5, v52
